# resid epilogue rewritten (dwordx4 via permlane16_swap, loads ahead) + scan MFMA fragment pipelining (both roles) + scan x-conv lane remap so x rows are read 4 lanes per row
# speedup vs baseline: 1.0728x; 1.0347x over previous
; #define PG8_STAGE(bufoff, gbase, voff) do { _Pragma("unroll") for (int _i = 0; _i < 2; ++_i) \
;     __builtin_amdgcn_global_load_lds((const unsigned*)((const char*)(gbase) + (voff)[_i]), (PG8_LAS unsigned*)(lds + (bufoff) + ldsw + _i * 8192), 16, 0, 0); } while (0)
; #define PG8_LDA(dst, b, h) do { _Pragma("unroll") for (int m = 0; m < 4; ++m) _Pragma("unroll") for (int k = 0; k < 2; ++k) dst[m][k] = *(const PG8_LAS bf16x8*)(lds + PG8_SA(b, h) + aoff + m * 2048 + k * 1024); } while (0)
; #define PG8_LDB(dst, b, h) do { _Pragma("unroll") for (int n = 0; n < 2; ++n) _Pragma("unroll") for (int k = 0; k < 2; ++k) dst[n][k] = *(const PG8_LAS bf16x8*)(lds + PG8_SB(b, h) + boff + n * 2048 + k * 1024); } while (0)
; #define PG8_MMA(ai, bj, At, Bt) do { __builtin_amdgcn_s_setprio(1); _Pragma("unroll") for (int m = 0; m < 4; ++m) _Pragma("unroll") for (int n = 0; n < 2; ++n) _Pragma("unroll") for (int k = 0; k < 2; ++k) \
;     acc[ai][bj][m][n] = __builtin_amdgcn_mfma_f32_16x16x32_bf16(Bt[n][k], At[m][k], acc[ai][bj][m][n], 0, 0, 0); __builtin_amdgcn_s_setprio(0); } while (0)
; #define PG8_WAIT_V(n) asm volatile("s_waitcnt vmcnt(" #n ")" ::: "memory")
; #define PG8_WAIT_L(n) asm volatile("s_waitcnt lgkmcnt(" #n ")" ::: "memory")
; #define PG8_BAR __builtin_amdgcn_s_barrier()
; #define PG8_SCHED __builtin_amdgcn_sched_barrier(0)
; template <class Epi>
; DI void gemm_phase(PG8_LAS unsigned char* lds, const Gemm g, const StaticOrder& S, const Epi& E) {
;     ...
;       PG8_LDB(B0, 0, 0); PG8_SCHED; PG8_LDA(At, 0, 0); PG8_STAGE(PG8_SA(1, 1), a1 + hstepA, voffA);
;       PG8_WAIT_L(8); PG8_BAR; PG8_WAIT_L(0); PG8_MMA(0, 0, At, B0); PG8_BAR; PG8_SCHED;
;       PG8_LDB(B1, 0, 1); PG8_STAGE(PG8_SB(0, 0), b2, voffB);
;       PG8_BAR; PG8_WAIT_L(0); PG8_MMA(0, 1, At, B1); PG8_BAR;
;       PG8_LDA(At, 0, 1); PG8_STAGE(PG8_SA(0, 0), a2, voffA);
;       PG8_BAR; PG8_WAIT_L(0); PG8_MMA(1, 0, At, B0); PG8_BAR; PG8_SCHED;
;       PG8_STAGE(PG8_SB(0, 1), b2 + hstepB, voffB);
;       PG8_WAIT_V(6); PG8_BAR; PG8_MMA(1, 1, At, B1); PG8_BAR;
.LBB0_835:
	s_add_i32 s81, s56, 2
	s_add_u32 s58, s44, 0x80
	s_addc_u32 s57, s45, 0
	s_add_i32 s82, 0, 0x10000
	v_add_u32_e32 v160, s82, v223
	ds_read_b128 v[130:133], v160
	ds_read_b128 v[152:155], v160 offset:1024
	ds_read_b128 v[156:159], v160 offset:2048
	ds_read_b128 v[160:163], v160 offset:3072
	s_cmp_eq_u32 s75, s56
	s_cselect_b32 s56, s0, s58
	s_cselect_b32 s57, s1, s57
	s_cselect_b32 s59, s55, s80
	s_cselect_b32 s58, s54, s79
	v_lshl_add_u64 v[196:197], s[44:45], 0, v[148:149]
	s_add_i32 m0, s66, 0xc000
	ds_read_b128 v[164:167], v225
	ds_read_b128 v[168:171], v225 offset:1024
	ds_read_b128 v[172:175], v225 offset:2048
	ds_read_b128 v[176:179], v225 offset:3072
	ds_read_b128 v[180:183], v225 offset:4096
	ds_read_b128 v[184:187], v225 offset:5120
	ds_read_b128 v[188:191], v225 offset:6144
	ds_read_b128 v[192:195], v225 offset:7168
	global_load_lds_dwordx4 v[196:197], off
	v_lshl_add_u64 v[196:197], s[44:45], 0, v[150:151]
	s_add_i32 m0, s66, 0xe000
	s_nop 0
	global_load_lds_dwordx4 v[196:197], off
	s_waitcnt lgkmcnt(8)
	s_barrier
	s_waitcnt lgkmcnt(0)
	s_setprio 1
	s_waitcnt lgkmcnt(0)
	v_mfma_f32_16x16x32_bf16 v[126:129], v[130:133], v[164:167], v[126:129]
	v_mfma_f32_16x16x32_bf16 v[122:125], v[156:159], v[164:167], v[122:125]
	v_mfma_f32_16x16x32_bf16 v[110:113], v[130:133], v[172:175], v[110:113]
	v_mfma_f32_16x16x32_bf16 v[106:109], v[156:159], v[172:175], v[106:109]
	v_mfma_f32_16x16x32_bf16 v[94:97], v[130:133], v[180:183], v[94:97]
	v_mfma_f32_16x16x32_bf16 v[90:93], v[156:159], v[180:183], v[90:93]
	v_mfma_f32_16x16x32_bf16 v[78:81], v[130:133], v[188:191], v[78:81]
	v_mfma_f32_16x16x32_bf16 v[74:77], v[156:159], v[188:191], v[74:77]
	v_mfma_f32_16x16x32_bf16 v[126:129], v[152:155], v[168:171], v[126:129]
	v_mfma_f32_16x16x32_bf16 v[122:125], v[160:163], v[168:171], v[122:125]
	v_mfma_f32_16x16x32_bf16 v[110:113], v[152:155], v[176:179], v[110:113]
	v_mfma_f32_16x16x32_bf16 v[106:109], v[160:163], v[176:179], v[106:109]
	v_mfma_f32_16x16x32_bf16 v[94:97], v[152:155], v[184:187], v[94:97]
	v_mfma_f32_16x16x32_bf16 v[90:93], v[160:163], v[184:187], v[90:93]
	v_mfma_f32_16x16x32_bf16 v[78:81], v[152:155], v[192:195], v[78:81]
	v_mfma_f32_16x16x32_bf16 v[74:77], v[160:163], v[192:195], v[74:77]
	s_setprio 0
	s_barrier
	s_add_i32 s83, 0, 0x14000
	s_add_i32 s82, s82, s65
	v_add_u32_e32 v234, s83, v223
	v_lshl_add_u64 v[238:239], s[58:59], 0, v[0:1]
	s_mov_b32 m0, s82
	ds_read_b128 v[196:199], v234
	ds_read_b128 v[226:229], v234 offset:1024
	ds_read_b128 v[230:233], v234 offset:2048
	ds_read_b128 v[234:237], v234 offset:3072
	global_load_lds_dwordx4 v[238:239], off
	v_lshl_add_u64 v[240:241], s[58:59], 0, v[142:143]
	s_add_i32 m0, s82, 0x2000
	s_nop 0
	global_load_lds_dwordx4 v[240:241], off
	s_barrier
	s_waitcnt lgkmcnt(0)
	s_setprio 1
	s_waitcnt lgkmcnt(0)
	v_mfma_f32_16x16x32_bf16 v[118:121], v[196:199], v[164:167], v[118:121]
	v_mfma_f32_16x16x32_bf16 v[114:117], v[230:233], v[164:167], v[114:117]
	v_mfma_f32_16x16x32_bf16 v[102:105], v[196:199], v[172:175], v[102:105]
	v_mfma_f32_16x16x32_bf16 v[98:101], v[230:233], v[172:175], v[98:101]
	v_mfma_f32_16x16x32_bf16 v[86:89], v[196:199], v[180:183], v[86:89]
	v_mfma_f32_16x16x32_bf16 v[82:85], v[230:233], v[180:183], v[82:85]
	v_mfma_f32_16x16x32_bf16 v[70:73], v[196:199], v[188:191], v[70:73]
	v_mfma_f32_16x16x32_bf16 v[66:69], v[230:233], v[188:191], v[66:69]
	v_mfma_f32_16x16x32_bf16 v[118:121], v[226:229], v[168:171], v[118:121]
	v_mfma_f32_16x16x32_bf16 v[114:117], v[234:237], v[168:171], v[114:117]
	v_mfma_f32_16x16x32_bf16 v[102:105], v[226:229], v[176:179], v[102:105]
	v_mfma_f32_16x16x32_bf16 v[98:101], v[234:237], v[176:179], v[98:101]
	v_mfma_f32_16x16x32_bf16 v[86:89], v[226:229], v[184:187], v[86:89]
	v_mfma_f32_16x16x32_bf16 v[82:85], v[234:237], v[184:187], v[82:85]
	v_mfma_f32_16x16x32_bf16 v[70:73], v[226:229], v[192:195], v[70:73]
	v_mfma_f32_16x16x32_bf16 v[66:69], v[234:237], v[192:195], v[66:69]
	s_setprio 0
	s_mov_b32 m0, s66
	v_lshl_add_u64 v[242:243], s[56:57], 0, v[146:147]
	s_barrier
	ds_read_b128 v[164:167], v225 offset:16384
	ds_read_b128 v[168:171], v225 offset:17408
	ds_read_b128 v[172:175], v225 offset:18432
	ds_read_b128 v[176:179], v225 offset:19456
	ds_read_b128 v[180:183], v225 offset:20480
	ds_read_b128 v[184:187], v225 offset:21504
	ds_read_b128 v[188:191], v225 offset:22528
	ds_read_b128 v[192:195], v225 offset:23552
	global_load_lds_dwordx4 v[242:243], off
	v_lshl_add_u64 v[244:245], s[56:57], 0, v[144:145]
	s_mov_b32 m0, s67
	s_nop 0
	global_load_lds_dwordx4 v[244:245], off
	s_barrier
	s_waitcnt lgkmcnt(0)
	s_setprio 1
	s_waitcnt lgkmcnt(0)
	v_mfma_f32_16x16x32_bf16 v[62:65], v[130:133], v[164:167], v[62:65]
	v_mfma_f32_16x16x32_bf16 v[58:61], v[156:159], v[164:167], v[58:61]
	v_mfma_f32_16x16x32_bf16 v[46:49], v[130:133], v[172:175], v[46:49]
	v_mfma_f32_16x16x32_bf16 v[42:45], v[156:159], v[172:175], v[42:45]
	v_mfma_f32_16x16x32_bf16 v[30:33], v[130:133], v[180:183], v[30:33]
	v_mfma_f32_16x16x32_bf16 v[26:29], v[156:159], v[180:183], v[26:29]
	v_mfma_f32_16x16x32_bf16 v[14:17], v[130:133], v[188:191], v[14:17]
	v_mfma_f32_16x16x32_bf16 v[10:13], v[156:159], v[188:191], v[10:13]
	v_mfma_f32_16x16x32_bf16 v[62:65], v[152:155], v[168:171], v[62:65]
	v_mfma_f32_16x16x32_bf16 v[58:61], v[160:163], v[168:171], v[58:61]
	v_mfma_f32_16x16x32_bf16 v[46:49], v[152:155], v[176:179], v[46:49]
	v_mfma_f32_16x16x32_bf16 v[42:45], v[160:163], v[176:179], v[42:45]
	v_mfma_f32_16x16x32_bf16 v[30:33], v[152:155], v[184:187], v[30:33]
	v_mfma_f32_16x16x32_bf16 v[26:29], v[160:163], v[184:187], v[26:29]
	v_mfma_f32_16x16x32_bf16 v[14:17], v[152:155], v[192:195], v[14:17]
	v_mfma_f32_16x16x32_bf16 v[10:13], v[160:163], v[192:195], v[10:13]
	s_setprio 0
	s_barrier
; #define PG8_STAGE(bufoff, gbase, voff) do { _Pragma("unroll") for (int _i = 0; _i < 2; ++_i) \
;     __builtin_amdgcn_global_load_lds((const unsigned*)((const char*)(gbase) + (voff)[_i]), (PG8_LAS unsigned*)(lds + (bufoff) + ldsw + _i * 8192), 16, 0, 0); } while (0)
; #define PG8_LDA(dst, b, h) do { _Pragma("unroll") for (int m = 0; m < 4; ++m) _Pragma("unroll") for (int k = 0; k < 2; ++k) dst[m][k] = *(const PG8_LAS bf16x8*)(lds + PG8_SA(b, h) + aoff + m * 2048 + k * 1024); } while (0)
; #define PG8_LDB(dst, b, h) do { _Pragma("unroll") for (int n = 0; n < 2; ++n) _Pragma("unroll") for (int k = 0; k < 2; ++k) dst[n][k] = *(const PG8_LAS bf16x8*)(lds + PG8_SB(b, h) + boff + n * 2048 + k * 1024); } while (0)
; #define PG8_MMA(ai, bj, At, Bt) do { __builtin_amdgcn_s_setprio(1); _Pragma("unroll") for (int m = 0; m < 4; ++m) _Pragma("unroll") for (int n = 0; n < 2; ++n) _Pragma("unroll") for (int k = 0; k < 2; ++k) \
;     acc[ai][bj][m][n] = __builtin_amdgcn_mfma_f32_16x16x32_bf16(Bt[n][k], At[m][k], acc[ai][bj][m][n], 0, 0, 0); __builtin_amdgcn_s_setprio(0); } while (0)
; #define PG8_WAIT_V(n) asm volatile("s_waitcnt vmcnt(" #n ")" ::: "memory")
; #define PG8_WAIT_L(n) asm volatile("s_waitcnt lgkmcnt(" #n ")" ::: "memory")
; #define PG8_BAR __builtin_amdgcn_s_barrier()
; #define PG8_SCHED __builtin_amdgcn_sched_barrier(0)
; template <class Epi>
; DI void gemm_phase(PG8_LAS unsigned char* lds, const Gemm g, const StaticOrder& S, const Epi& E) {
;     ...
;       PG8_STAGE(PG8_SB(0, 1), b2 + hstepB, voffB);
;       PG8_WAIT_V(6); PG8_BAR; PG8_MMA(1, 1, At, B1); PG8_BAR;
;       PG8_LDB(B0, 1, 0); PG8_SCHED; PG8_LDA(At, 1, 0); PG8_STAGE(PG8_SA(0, 1), a2 + hstepA, voffA);
;       PG8_WAIT_L(8); PG8_BAR; PG8_WAIT_L(0); PG8_MMA(0, 0, At, B0); PG8_BAR; PG8_SCHED;
;       PG8_LDB(B1, 1, 1); PG8_STAGE(PG8_SB(1, 0), b3, voffB);
;       PG8_BAR; PG8_WAIT_L(0); PG8_MMA(0, 1, At, B1); PG8_BAR;
;       PG8_LDA(At, 1, 1); PG8_STAGE(PG8_SA(1, 0), a3, voffA);
;       PG8_BAR; PG8_WAIT_L(0); PG8_MMA(1, 0, At, B0); PG8_BAR; PG8_SCHED;
	s_add_u32 s58, s58, s62
	s_addc_u32 s59, s59, 0
	s_add_i32 s82, s83, s65
	v_lshl_add_u64 v[246:247], s[58:59], 0, v[0:1]
	s_mov_b32 m0, s82
	v_lshl_add_u64 v[248:249], s[58:59], 0, v[142:143]
	global_load_lds_dwordx4 v[246:247], off
	s_add_i32 m0, s82, 0x2000
	s_nop 0
	global_load_lds_dwordx4 v[248:249], off
	s_waitcnt vmcnt(6)
	s_barrier
	s_setprio 1
	v_mfma_f32_16x16x32_bf16 v[54:57], v[196:199], v[164:167], v[54:57]
	v_mfma_f32_16x16x32_bf16 v[50:53], v[230:233], v[164:167], v[50:53]
	v_mfma_f32_16x16x32_bf16 v[38:41], v[196:199], v[172:175], v[38:41]
	v_mfma_f32_16x16x32_bf16 v[34:37], v[230:233], v[172:175], v[34:37]
	v_mfma_f32_16x16x32_bf16 v[22:25], v[196:199], v[180:183], v[22:25]
	v_mfma_f32_16x16x32_bf16 v[18:21], v[230:233], v[180:183], v[18:21]
	v_mfma_f32_16x16x32_bf16 v[6:9], v[196:199], v[188:191], v[6:9]
	v_mfma_f32_16x16x32_bf16 v[2:5], v[230:233], v[188:191], v[2:5]
	v_mfma_f32_16x16x32_bf16 v[54:57], v[226:229], v[168:171], v[54:57]
	v_mfma_f32_16x16x32_bf16 v[50:53], v[234:237], v[168:171], v[50:53]
	v_mfma_f32_16x16x32_bf16 v[38:41], v[226:229], v[176:179], v[38:41]
	v_mfma_f32_16x16x32_bf16 v[34:37], v[234:237], v[176:179], v[34:37]
	v_mfma_f32_16x16x32_bf16 v[22:25], v[226:229], v[184:187], v[22:25]
	v_mfma_f32_16x16x32_bf16 v[18:21], v[234:237], v[184:187], v[18:21]
	v_mfma_f32_16x16x32_bf16 v[6:9], v[226:229], v[192:195], v[6:9]
	v_mfma_f32_16x16x32_bf16 v[2:5], v[234:237], v[192:195], v[2:5]
	s_setprio 0
	s_add_i32 s58, 0, 0x18000
	v_add_u32_e32 v160, s58, v223
	s_barrier
	ds_read_b128 v[130:133], v160
	ds_read_b128 v[152:155], v160 offset:1024
	ds_read_b128 v[156:159], v160 offset:2048
	ds_read_b128 v[160:163], v160 offset:3072
	s_add_u32 s56, s56, s50
	s_addc_u32 s57, s57, 0
	s_mov_b32 m0, s68
	v_lshl_add_u64 v[196:197], s[56:57], 0, v[146:147]
	ds_read_b128 v[164:167], v225 offset:32768
	ds_read_b128 v[168:171], v225 offset:33792
	ds_read_b128 v[172:175], v225 offset:34816
	ds_read_b128 v[176:179], v225 offset:35840
	ds_read_b128 v[180:183], v225 offset:36864
	ds_read_b128 v[184:187], v225 offset:37888
	ds_read_b128 v[188:191], v225 offset:38912
	ds_read_b128 v[192:195], v225 offset:39936
	global_load_lds_dwordx4 v[196:197], off
	v_lshl_add_u64 v[196:197], s[56:57], 0, v[144:145]
	s_mov_b32 m0, s69
	s_nop 0
	global_load_lds_dwordx4 v[196:197], off
	s_waitcnt lgkmcnt(8)
	s_barrier
	s_waitcnt lgkmcnt(0)
	s_setprio 1
	s_waitcnt lgkmcnt(0)
	v_mfma_f32_16x16x32_bf16 v[126:129], v[130:133], v[164:167], v[126:129]
	v_mfma_f32_16x16x32_bf16 v[122:125], v[156:159], v[164:167], v[122:125]
	v_mfma_f32_16x16x32_bf16 v[110:113], v[130:133], v[172:175], v[110:113]
	v_mfma_f32_16x16x32_bf16 v[106:109], v[156:159], v[172:175], v[106:109]
	v_mfma_f32_16x16x32_bf16 v[94:97], v[130:133], v[180:183], v[94:97]
	v_mfma_f32_16x16x32_bf16 v[90:93], v[156:159], v[180:183], v[90:93]
	v_mfma_f32_16x16x32_bf16 v[78:81], v[130:133], v[188:191], v[78:81]
	v_mfma_f32_16x16x32_bf16 v[74:77], v[156:159], v[188:191], v[74:77]
	v_mfma_f32_16x16x32_bf16 v[126:129], v[152:155], v[168:171], v[126:129]
	v_mfma_f32_16x16x32_bf16 v[122:125], v[160:163], v[168:171], v[122:125]
	v_mfma_f32_16x16x32_bf16 v[110:113], v[152:155], v[176:179], v[110:113]
	v_mfma_f32_16x16x32_bf16 v[106:109], v[160:163], v[176:179], v[106:109]
	v_mfma_f32_16x16x32_bf16 v[94:97], v[152:155], v[184:187], v[94:97]
	v_mfma_f32_16x16x32_bf16 v[90:93], v[160:163], v[184:187], v[90:93]
	v_mfma_f32_16x16x32_bf16 v[78:81], v[152:155], v[192:195], v[78:81]
	v_mfma_f32_16x16x32_bf16 v[74:77], v[160:163], v[192:195], v[74:77]
	s_setprio 0
	s_barrier
	s_add_i32 s56, 0, 0x1c000
	s_add_i32 s57, s58, s65
	v_add_u32_e32 v234, s56, v223
	v_lshl_add_u64 v[238:239], v[238:239], 0, s[86:87]
	s_mov_b32 m0, s57
	ds_read_b128 v[196:199], v234
	ds_read_b128 v[226:229], v234 offset:1024
	ds_read_b128 v[230:233], v234 offset:2048
	ds_read_b128 v[234:237], v234 offset:3072
	global_load_lds_dwordx4 v[238:239], off
	v_lshl_add_u64 v[238:239], v[240:241], 0, s[86:87]
	s_add_i32 m0, s57, 0x2000
	s_nop 0
	global_load_lds_dwordx4 v[238:239], off
	s_barrier
	s_waitcnt lgkmcnt(0)
	s_setprio 1
	s_waitcnt lgkmcnt(0)
	v_mfma_f32_16x16x32_bf16 v[118:121], v[196:199], v[164:167], v[118:121]
	v_mfma_f32_16x16x32_bf16 v[114:117], v[230:233], v[164:167], v[114:117]
	v_mfma_f32_16x16x32_bf16 v[102:105], v[196:199], v[172:175], v[102:105]
	v_mfma_f32_16x16x32_bf16 v[98:101], v[230:233], v[172:175], v[98:101]
	v_mfma_f32_16x16x32_bf16 v[86:89], v[196:199], v[180:183], v[86:89]
	v_mfma_f32_16x16x32_bf16 v[82:85], v[230:233], v[180:183], v[82:85]
	v_mfma_f32_16x16x32_bf16 v[70:73], v[196:199], v[188:191], v[70:73]
	v_mfma_f32_16x16x32_bf16 v[66:69], v[230:233], v[188:191], v[66:69]
	v_mfma_f32_16x16x32_bf16 v[118:121], v[226:229], v[168:171], v[118:121]
	v_mfma_f32_16x16x32_bf16 v[114:117], v[234:237], v[168:171], v[114:117]
	v_mfma_f32_16x16x32_bf16 v[102:105], v[226:229], v[176:179], v[102:105]
	v_mfma_f32_16x16x32_bf16 v[98:101], v[234:237], v[176:179], v[98:101]
	v_mfma_f32_16x16x32_bf16 v[86:89], v[226:229], v[184:187], v[86:89]
	v_mfma_f32_16x16x32_bf16 v[82:85], v[234:237], v[184:187], v[82:85]
	v_mfma_f32_16x16x32_bf16 v[70:73], v[226:229], v[192:195], v[70:73]
	v_mfma_f32_16x16x32_bf16 v[66:69], v[234:237], v[192:195], v[66:69]
	s_setprio 0
	s_mov_b32 m0, s72
	v_lshl_add_u64 v[238:239], v[242:243], 0, s[86:87]
	s_barrier
	ds_read_b128 v[164:167], v225 offset:49152
	ds_read_b128 v[168:171], v225 offset:50176
	ds_read_b128 v[172:175], v225 offset:51200
	ds_read_b128 v[176:179], v225 offset:52224
	ds_read_b128 v[180:183], v225 offset:53248
	ds_read_b128 v[184:187], v225 offset:54272
	ds_read_b128 v[188:191], v225 offset:55296
	ds_read_b128 v[192:195], v225 offset:56320
	global_load_lds_dwordx4 v[238:239], off
	v_lshl_add_u64 v[238:239], v[244:245], 0, s[86:87]
	s_mov_b32 m0, s73
	s_nop 0
	global_load_lds_dwordx4 v[238:239], off
	s_barrier
; DI unsigned pk2(float lo, float hi) { f32x2 v = {lo, hi}; bf2_t r = __builtin_convertvector(v, bf2_t); return __builtin_bit_cast(unsigned, r); }
; DI float bflo(unsigned u) { return __uint_as_float(u << 16); }
; DI float bfhi(unsigned u) { return __uint_as_float(u & 0xffff0000u); }
;   DI void operator()(const f32x4 (&acc)[2][2][4][2], const Unit& u, int wr, int wc, int fr, int fq, const PG8_LAS float* sR) const {
;     const int row0 = u.pm * BM + wr * 64 + fr, col0 = u.pn * BM + wc * 32 + 4 * fq;
; #pragma unroll
;     for (int ai = 0; ai < 2; ++ai) {
;       u32x2 sv[4][2][2];
;       if (X0 == nullptr) {
; #pragma unroll
;         for (int m = 0; m < 4; ++m)
; #pragma unroll
;           for (int bj = 0; bj < 2; ++bj)
; #pragma unroll
;             for (int n = 0; n < 2; ++n) sv[m][bj][n] = *(const u32x2*)(S + (size_t)(row0 + ai * HALF + m * 16) * 1024 + col0 + bj * HALF + n * 16);
;       } else {
; #pragma unroll
;         for (int m = 0; m < 4; ++m)
; #pragma unroll
;           for (int bj = 0; bj < 2; ++bj)
; #pragma unroll
;             for (int n = 0; n < 2; ++n) sv[m][bj][n] = (u32x2){0u, 0u};
;       }
; #pragma unroll
;       for (int m = 0; m < 4; ++m) {
;         const int row = row0 + ai * HALF + m * 16;
;         const size_t ro = (size_t)row * 1024 + col0;
;         float ss = 0.f;
; #pragma unroll
;         for (int bj = 0; bj < 2; ++bj)
; #pragma unroll
;           for (int n = 0; n < 2; ++n) {
;             f32x4 v;
;             if (X0 != nullptr) v = *(const f32x4*)(X0 + ro + bj * HALF + n * 16);
;             else { const u32x2 q = sv[m][bj][n]; v[0] = bflo(q[0]); v[1] = bfhi(q[0]); v[2] = bflo(q[1]); v[3] = bfhi(q[1]); }
;             v += acc[ai][bj][m][n];
;             ss += v[0] * v[0] + v[1] * v[1] + v[2] * v[2] + v[3] * v[3];
;             if (!dry) { u32x2 q; q[0] = pk2(v[0], v[1]); q[1] = pk2(v[2], v[3]); *(u32x2*)(S + ro + bj * HALF + n * 16) = q; }
;           }
;         ss += __shfl_xor(ss, 16); ss += __shfl_xor(ss, 32);
;         if (!dry && fq == 0) ssq[(size_t)row * 16 + u.pn * 4 + wc] = ss;
; template <class Epi>
; DI void gemm_phase(PG8_LAS unsigned char* lds, const Gemm g, const StaticOrder& S, const Epi& E) {
;     ...
;       PG8_BAR; PG8_WAIT_L(0); PG8_MMA(1, 0, At, B0); PG8_BAR; PG8_SCHED;
;       PG8_STAGE(PG8_SB(1, 1), b3 + hstepB, voffB);
;       PG8_WAIT_V(6); PG8_BAR; PG8_MMA(1, 1, At, B1); PG8_BAR;
	s_waitcnt lgkmcnt(0)
	s_setprio 1
	s_waitcnt lgkmcnt(0)
	v_mfma_f32_16x16x32_bf16 v[62:65], v[130:133], v[164:167], v[62:65]
	v_mfma_f32_16x16x32_bf16 v[58:61], v[156:159], v[164:167], v[58:61]
	v_mfma_f32_16x16x32_bf16 v[46:49], v[130:133], v[172:175], v[46:49]
	v_mfma_f32_16x16x32_bf16 v[42:45], v[156:159], v[172:175], v[42:45]
	v_mfma_f32_16x16x32_bf16 v[30:33], v[130:133], v[180:183], v[30:33]
	v_mfma_f32_16x16x32_bf16 v[26:29], v[156:159], v[180:183], v[26:29]
	v_mfma_f32_16x16x32_bf16 v[14:17], v[130:133], v[188:191], v[14:17]
	v_mfma_f32_16x16x32_bf16 v[10:13], v[156:159], v[188:191], v[10:13]
	v_mfma_f32_16x16x32_bf16 v[62:65], v[152:155], v[168:171], v[62:65]
	v_mfma_f32_16x16x32_bf16 v[58:61], v[160:163], v[168:171], v[58:61]
	v_mfma_f32_16x16x32_bf16 v[46:49], v[152:155], v[176:179], v[46:49]
	v_mfma_f32_16x16x32_bf16 v[42:45], v[160:163], v[176:179], v[42:45]
	v_mfma_f32_16x16x32_bf16 v[30:33], v[152:155], v[184:187], v[30:33]
	v_mfma_f32_16x16x32_bf16 v[26:29], v[160:163], v[184:187], v[26:29]
	v_mfma_f32_16x16x32_bf16 v[14:17], v[152:155], v[192:195], v[14:17]
	v_mfma_f32_16x16x32_bf16 v[10:13], v[160:163], v[192:195], v[10:13]
	s_setprio 0
	s_barrier
	s_add_i32 s56, s56, s65
	v_lshl_add_u64 v[130:131], v[246:247], 0, s[86:87]
	s_mov_b32 m0, s56
	s_nop 0
	global_load_lds_dwordx4 v[130:131], off
	v_lshl_add_u64 v[130:131], v[248:249], 0, s[86:87]
	s_add_i32 m0, s56, 0x2000
	s_nop 0
	global_load_lds_dwordx4 v[130:131], off
	s_waitcnt vmcnt(6)
	s_barrier
	s_setprio 1
	v_mfma_f32_16x16x32_bf16 v[54:57], v[196:199], v[164:167], v[54:57]
	v_mfma_f32_16x16x32_bf16 v[50:53], v[230:233], v[164:167], v[50:53]
	v_mfma_f32_16x16x32_bf16 v[38:41], v[196:199], v[172:175], v[38:41]
	v_mfma_f32_16x16x32_bf16 v[34:37], v[230:233], v[172:175], v[34:37]
	v_mfma_f32_16x16x32_bf16 v[22:25], v[196:199], v[180:183], v[22:25]
	v_mfma_f32_16x16x32_bf16 v[18:21], v[230:233], v[180:183], v[18:21]
	v_mfma_f32_16x16x32_bf16 v[6:9], v[196:199], v[188:191], v[6:9]
	v_mfma_f32_16x16x32_bf16 v[2:5], v[230:233], v[188:191], v[2:5]
	v_mfma_f32_16x16x32_bf16 v[54:57], v[226:229], v[168:171], v[54:57]
	v_mfma_f32_16x16x32_bf16 v[50:53], v[234:237], v[168:171], v[50:53]
	v_mfma_f32_16x16x32_bf16 v[38:41], v[226:229], v[176:179], v[38:41]
	v_mfma_f32_16x16x32_bf16 v[34:37], v[234:237], v[176:179], v[34:37]
	v_mfma_f32_16x16x32_bf16 v[22:25], v[226:229], v[184:187], v[22:25]
	v_mfma_f32_16x16x32_bf16 v[18:21], v[234:237], v[184:187], v[18:21]
	v_mfma_f32_16x16x32_bf16 v[6:9], v[226:229], v[192:195], v[6:9]
	v_mfma_f32_16x16x32_bf16 v[2:5], v[234:237], v[192:195], v[2:5]
	s_setprio 0
	s_add_u32 s44, s44, 0x100
	s_addc_u32 s45, s45, 0
	s_add_u32 s79, s79, 0x100
	s_addc_u32 s80, s80, 0
	s_cmp_ge_u32 s81, s71
	s_mov_b32 s56, s81
	s_barrier
	s_cbranch_scc0 .LBB0_835
	s_and_b64 vcc, exec, s[52:53]
	s_cbranch_vccnz .Lres_x0_path
	v_lshl_add_u32 v152, s78, 8, v222
	v_and_b32_e32 v153, 4, v224
	v_lshl_or_b32 v154, s34, 8, v224
	v_mad_u32_u24 v154, v153, 3, v154
	v_lshlrev_b32_e32 v153, 10, v152
	v_add_u32_e32 v154, v154, v153
	v_mov_b32_e32 v155, 0
	v_lshl_add_u64 v[132:133], v[154:155], 1, s[22:23]
	v_mov_b64_e32 v[130:131], v[132:133]
	v_lshlrev_b32_e32 v154, 6, v152
	s_lshl_b32 s56, s34, 4
	s_lshl_b32 s57, s70, 2
	s_add_i32 s56, s56, s57
	v_add_u32_e32 v154, s56, v154
	v_lshl_add_u64 v[250:251], v[154:155], 0, s[92:93]
	s_mov_b32 s57, 0
	global_load_dwordx4 v[152:155], v[130:131], off
	global_load_dwordx4 v[156:159], v[130:131], off offset:256
	s_mov_b32 s56, 0x8000
	v_lshl_add_u64 v[130:131], v[130:131], 0, s[56:57]
	global_load_dwordx4 v[160:163], v[130:131], off
	global_load_dwordx4 v[164:167], v[130:131], off offset:256
	s_mov_b32 s56, 0x8000
	v_lshl_add_u64 v[130:131], v[130:131], 0, s[56:57]
	global_load_dwordx4 v[168:171], v[130:131], off
	global_load_dwordx4 v[172:175], v[130:131], off offset:256
	s_mov_b32 s56, 0x8000
	v_lshl_add_u64 v[130:131], v[130:131], 0, s[56:57]
	global_load_dwordx4 v[176:179], v[130:131], off
	global_load_dwordx4 v[180:183], v[130:131], off offset:256
	s_mov_b32 s56, 0x28000
	v_lshl_add_u64 v[130:131], v[130:131], 0, s[56:57]
	global_load_dwordx4 v[184:187], v[130:131], off
	global_load_dwordx4 v[188:191], v[130:131], off offset:256
	s_mov_b32 s56, 0x8000
	v_lshl_add_u64 v[130:131], v[130:131], 0, s[56:57]
	global_load_dwordx4 v[192:195], v[130:131], off
	global_load_dwordx4 v[196:199], v[130:131], off offset:256
	s_mov_b32 s56, 0x8000
	v_lshl_add_u64 v[130:131], v[130:131], 0, s[56:57]
	global_load_dwordx4 v[226:229], v[130:131], off
	global_load_dwordx4 v[230:233], v[130:131], off offset:256
	s_mov_b32 s56, 0x8000
	v_lshl_add_u64 v[130:131], v[130:131], 0, s[56:57]
	global_load_dwordx4 v[234:237], v[130:131], off
	global_load_dwordx4 v[238:241], v[130:131], off offset:256
	v_permlane16_swap_b32_e32 v126, v122
	v_permlane16_swap_b32_e32 v127, v123
	v_permlane16_swap_b32_e32 v128, v124
	v_permlane16_swap_b32_e32 v129, v125
	v_permlane16_swap_b32_e32 v118, v114
	v_permlane16_swap_b32_e32 v119, v115
	v_permlane16_swap_b32_e32 v120, v116
	v_permlane16_swap_b32_e32 v121, v117
	v_permlane16_swap_b32_e32 v110, v106
	v_permlane16_swap_b32_e32 v111, v107
	v_permlane16_swap_b32_e32 v112, v108
	v_permlane16_swap_b32_e32 v113, v109
	v_permlane16_swap_b32_e32 v102, v98
	v_permlane16_swap_b32_e32 v103, v99
	v_permlane16_swap_b32_e32 v104, v100
	v_permlane16_swap_b32_e32 v105, v101
	v_permlane16_swap_b32_e32 v94, v90
	v_permlane16_swap_b32_e32 v95, v91
	v_permlane16_swap_b32_e32 v96, v92
	v_permlane16_swap_b32_e32 v97, v93
	v_permlane16_swap_b32_e32 v86, v82
	v_permlane16_swap_b32_e32 v87, v83
	v_permlane16_swap_b32_e32 v88, v84
; DI unsigned pk2(float lo, float hi) { f32x2 v = {lo, hi}; bf2_t r = __builtin_convertvector(v, bf2_t); return __builtin_bit_cast(unsigned, r); }
; DI float bflo(unsigned u) { return __uint_as_float(u << 16); }
; DI float bfhi(unsigned u) { return __uint_as_float(u & 0xffff0000u); }
; #define PG8_LAS __attribute__((address_space(3)))
;   DI void operator()(const f32x4 (&acc)[2][2][4][2], const Unit& u, int wr, int wc, int fr, int fq, const PG8_LAS float* sR) const {
;     const int row0 = u.pm * BM + wr * 64 + fr, col0 = u.pn * BM + wc * 32 + 4 * fq;
; #pragma unroll
;     for (int ai = 0; ai < 2; ++ai) {
;       u32x2 sv[4][2][2];
;       if (X0 == nullptr) {
; #pragma unroll
;         for (int m = 0; m < 4; ++m)
; #pragma unroll
;           for (int bj = 0; bj < 2; ++bj)
; #pragma unroll
;             for (int n = 0; n < 2; ++n) sv[m][bj][n] = *(const u32x2*)(S + (size_t)(row0 + ai * HALF + m * 16) * 1024 + col0 + bj * HALF + n * 16);
;       } else {
; #pragma unroll
;         for (int m = 0; m < 4; ++m)
; #pragma unroll
;           for (int bj = 0; bj < 2; ++bj)
; #pragma unroll
;             for (int n = 0; n < 2; ++n) sv[m][bj][n] = (u32x2){0u, 0u};
;       }
; #pragma unroll
;       for (int m = 0; m < 4; ++m) {
;         const int row = row0 + ai * HALF + m * 16;
;         const size_t ro = (size_t)row * 1024 + col0;
;         float ss = 0.f;
; #pragma unroll
;         for (int bj = 0; bj < 2; ++bj)
; #pragma unroll
;           for (int n = 0; n < 2; ++n) {
;             f32x4 v;
;             if (X0 != nullptr) v = *(const f32x4*)(X0 + ro + bj * HALF + n * 16);
;             else { const u32x2 q = sv[m][bj][n]; v[0] = bflo(q[0]); v[1] = bfhi(q[0]); v[2] = bflo(q[1]); v[3] = bfhi(q[1]); }
;             v += acc[ai][bj][m][n];
;             ss += v[0] * v[0] + v[1] * v[1] + v[2] * v[2] + v[3] * v[3];
;             if (!dry) { u32x2 q; q[0] = pk2(v[0], v[1]); q[1] = pk2(v[2], v[3]); *(u32x2*)(S + ro + bj * HALF + n * 16) = q; }
;           }
;         ss += __shfl_xor(ss, 16); ss += __shfl_xor(ss, 32);
;         if (!dry && fq == 0) ssq[(size_t)row * 16 + u.pn * 4 + wc] = ss;
	v_permlane16_swap_b32_e32 v89, v85
	v_permlane16_swap_b32_e32 v78, v74
	v_permlane16_swap_b32_e32 v79, v75
	v_permlane16_swap_b32_e32 v80, v76
	v_permlane16_swap_b32_e32 v81, v77
	v_permlane16_swap_b32_e32 v70, v66
	v_permlane16_swap_b32_e32 v71, v67
	v_permlane16_swap_b32_e32 v72, v68
	v_permlane16_swap_b32_e32 v73, v69
	v_permlane16_swap_b32_e32 v62, v58
	v_permlane16_swap_b32_e32 v63, v59
	v_permlane16_swap_b32_e32 v64, v60
	v_permlane16_swap_b32_e32 v65, v61
	v_permlane16_swap_b32_e32 v54, v50
	v_permlane16_swap_b32_e32 v55, v51
	v_permlane16_swap_b32_e32 v56, v52
	v_permlane16_swap_b32_e32 v57, v53
	v_permlane16_swap_b32_e32 v46, v42
	v_permlane16_swap_b32_e32 v47, v43
	v_permlane16_swap_b32_e32 v48, v44
	v_permlane16_swap_b32_e32 v49, v45
	v_permlane16_swap_b32_e32 v38, v34
	v_permlane16_swap_b32_e32 v39, v35
	v_permlane16_swap_b32_e32 v40, v36
	v_permlane16_swap_b32_e32 v41, v37
	v_permlane16_swap_b32_e32 v30, v26
	v_permlane16_swap_b32_e32 v31, v27
	v_permlane16_swap_b32_e32 v32, v28
	v_permlane16_swap_b32_e32 v33, v29
	v_permlane16_swap_b32_e32 v22, v18
	v_permlane16_swap_b32_e32 v23, v19
	v_permlane16_swap_b32_e32 v24, v20
	v_permlane16_swap_b32_e32 v25, v21
	v_permlane16_swap_b32_e32 v14, v10
	v_permlane16_swap_b32_e32 v15, v11
	v_permlane16_swap_b32_e32 v16, v12
	v_permlane16_swap_b32_e32 v17, v13
	v_permlane16_swap_b32_e32 v6, v2
	v_permlane16_swap_b32_e32 v7, v3
	v_permlane16_swap_b32_e32 v8, v4
	v_permlane16_swap_b32_e32 v9, v5
	s_waitcnt vmcnt(15)
	v_lshlrev_b32_e32 v242, 16, v152
	v_and_b32_e32 v243, 0xffff0000, v152
	v_lshlrev_b32_e32 v244, 16, v153
	v_and_b32_e32 v245, 0xffff0000, v153
	v_lshlrev_b32_e32 v246, 16, v154
	v_and_b32_e32 v247, 0xffff0000, v154
	v_lshlrev_b32_e32 v248, 16, v155
	v_and_b32_e32 v249, 0xffff0000, v155
	v_pk_add_f32 v[126:127], v[126:127], v[242:243]
	v_pk_add_f32 v[128:129], v[128:129], v[244:245]
	v_pk_add_f32 v[122:123], v[122:123], v[246:247]
	v_pk_add_f32 v[124:125], v[124:125], v[248:249]
	v_mul_f32_e32 v130, v126, v126
	v_mul_f32_e32 v131, v127, v127
	v_fmac_f32_e32 v130, v128, v128
	v_fmac_f32_e32 v131, v129, v129
	v_fmac_f32_e32 v130, v122, v122
	v_fmac_f32_e32 v131, v123, v123
	v_fmac_f32_e32 v130, v124, v124
	v_fmac_f32_e32 v131, v125, v125
	v_cvt_pk_bf16_f32 v126, v126, v127
	v_cvt_pk_bf16_f32 v127, v128, v129
	v_cvt_pk_bf16_f32 v128, v122, v123
	v_cvt_pk_bf16_f32 v129, v124, v125
	global_store_dwordx4 v[132:133], v[126:129], off
	s_waitcnt vmcnt(15)
	v_lshlrev_b32_e32 v242, 16, v156
	v_and_b32_e32 v243, 0xffff0000, v156
	v_lshlrev_b32_e32 v244, 16, v157
	v_and_b32_e32 v245, 0xffff0000, v157
	v_lshlrev_b32_e32 v246, 16, v158
	v_and_b32_e32 v247, 0xffff0000, v158
	v_lshlrev_b32_e32 v248, 16, v159
	v_and_b32_e32 v249, 0xffff0000, v159
	v_pk_add_f32 v[118:119], v[118:119], v[242:243]
	v_pk_add_f32 v[120:121], v[120:121], v[244:245]
	v_pk_add_f32 v[114:115], v[114:115], v[246:247]
	v_pk_add_f32 v[116:117], v[116:117], v[248:249]
	v_fmac_f32_e32 v130, v118, v118
	v_fmac_f32_e32 v131, v119, v119
	v_fmac_f32_e32 v130, v120, v120
	v_fmac_f32_e32 v131, v121, v121
	v_fmac_f32_e32 v130, v114, v114
	v_fmac_f32_e32 v131, v115, v115
	v_fmac_f32_e32 v130, v116, v116
	v_fmac_f32_e32 v131, v117, v117
	v_cvt_pk_bf16_f32 v118, v118, v119
	v_cvt_pk_bf16_f32 v119, v120, v121
	v_cvt_pk_bf16_f32 v120, v114, v115
	v_cvt_pk_bf16_f32 v121, v116, v117
	global_store_dwordx4 v[132:133], v[118:121], off offset:256
	s_mov_b32 s56, 0x8000
	v_lshl_add_u64 v[132:133], v[132:133], 0, s[56:57]
	v_add_f32_e32 v130, v130, v131
	v_mov_b32_e32 v131, v130
	s_nop 1
	v_permlane16_swap_b32_e32 v130, v131
	s_nop 1
	v_add_f32_e32 v130, v130, v131
	v_mov_b32_e32 v131, v130
	s_nop 1
	v_permlane32_swap_b32_e32 v130, v131
	s_nop 1
	v_add_f32_e32 v130, v130, v131
	s_and_saveexec_b64 s[58:59], s[40:41]
	global_store_dword v[250:251], v130, off
	s_or_b64 exec, exec, s[58:59]
	s_mov_b32 s56, 0x400
	v_lshl_add_u64 v[250:251], v[250:251], 0, s[56:57]
	s_waitcnt vmcnt(16)
	v_lshlrev_b32_e32 v242, 16, v160
	v_and_b32_e32 v243, 0xffff0000, v160
	v_lshlrev_b32_e32 v244, 16, v161
	v_and_b32_e32 v245, 0xffff0000, v161
	v_lshlrev_b32_e32 v246, 16, v162
	v_and_b32_e32 v247, 0xffff0000, v162
	v_lshlrev_b32_e32 v248, 16, v163
	v_and_b32_e32 v249, 0xffff0000, v163
	v_pk_add_f32 v[110:111], v[110:111], v[242:243]
	v_pk_add_f32 v[112:113], v[112:113], v[244:245]
	v_pk_add_f32 v[106:107], v[106:107], v[246:247]
	v_pk_add_f32 v[108:109], v[108:109], v[248:249]
	v_mul_f32_e32 v130, v110, v110
	v_mul_f32_e32 v131, v111, v111
	v_fmac_f32_e32 v130, v112, v112
	v_fmac_f32_e32 v131, v113, v113
	v_fmac_f32_e32 v130, v106, v106
	v_fmac_f32_e32 v131, v107, v107
	v_fmac_f32_e32 v130, v108, v108
	v_fmac_f32_e32 v131, v109, v109
	v_cvt_pk_bf16_f32 v110, v110, v111
	v_cvt_pk_bf16_f32 v111, v112, v113
	v_cvt_pk_bf16_f32 v112, v106, v107
	v_cvt_pk_bf16_f32 v113, v108, v109
	global_store_dwordx4 v[132:133], v[110:113], off
	s_waitcnt vmcnt(16)
; DI unsigned pk2(float lo, float hi) { f32x2 v = {lo, hi}; bf2_t r = __builtin_convertvector(v, bf2_t); return __builtin_bit_cast(unsigned, r); }
; DI float bflo(unsigned u) { return __uint_as_float(u << 16); }
; DI float bfhi(unsigned u) { return __uint_as_float(u & 0xffff0000u); }
; #define PG8_LAS __attribute__((address_space(3)))
;   DI void operator()(const f32x4 (&acc)[2][2][4][2], const Unit& u, int wr, int wc, int fr, int fq, const PG8_LAS float* sR) const {
;     const int row0 = u.pm * BM + wr * 64 + fr, col0 = u.pn * BM + wc * 32 + 4 * fq;
; #pragma unroll
;     for (int ai = 0; ai < 2; ++ai) {
;       u32x2 sv[4][2][2];
;       if (X0 == nullptr) {
; #pragma unroll
;         for (int m = 0; m < 4; ++m)
; #pragma unroll
;           for (int bj = 0; bj < 2; ++bj)
; #pragma unroll
;             for (int n = 0; n < 2; ++n) sv[m][bj][n] = *(const u32x2*)(S + (size_t)(row0 + ai * HALF + m * 16) * 1024 + col0 + bj * HALF + n * 16);
;       } else {
; #pragma unroll
;         for (int m = 0; m < 4; ++m)
; #pragma unroll
;           for (int bj = 0; bj < 2; ++bj)
; #pragma unroll
;             for (int n = 0; n < 2; ++n) sv[m][bj][n] = (u32x2){0u, 0u};
;       }
; #pragma unroll
;       for (int m = 0; m < 4; ++m) {
;         const int row = row0 + ai * HALF + m * 16;
;         const size_t ro = (size_t)row * 1024 + col0;
;         float ss = 0.f;
; #pragma unroll
;         for (int bj = 0; bj < 2; ++bj)
; #pragma unroll
;           for (int n = 0; n < 2; ++n) {
;             f32x4 v;
;             if (X0 != nullptr) v = *(const f32x4*)(X0 + ro + bj * HALF + n * 16);
;             else { const u32x2 q = sv[m][bj][n]; v[0] = bflo(q[0]); v[1] = bfhi(q[0]); v[2] = bflo(q[1]); v[3] = bfhi(q[1]); }
;             v += acc[ai][bj][m][n];
;             ss += v[0] * v[0] + v[1] * v[1] + v[2] * v[2] + v[3] * v[3];
;             if (!dry) { u32x2 q; q[0] = pk2(v[0], v[1]); q[1] = pk2(v[2], v[3]); *(u32x2*)(S + ro + bj * HALF + n * 16) = q; }
;           }
;         ss += __shfl_xor(ss, 16); ss += __shfl_xor(ss, 32);
;         if (!dry && fq == 0) ssq[(size_t)row * 16 + u.pn * 4 + wc] = ss;
	v_lshlrev_b32_e32 v242, 16, v164
	v_and_b32_e32 v243, 0xffff0000, v164
	v_lshlrev_b32_e32 v244, 16, v165
	v_and_b32_e32 v245, 0xffff0000, v165
	v_lshlrev_b32_e32 v246, 16, v166
	v_and_b32_e32 v247, 0xffff0000, v166
	v_lshlrev_b32_e32 v248, 16, v167
	v_and_b32_e32 v249, 0xffff0000, v167
	v_pk_add_f32 v[102:103], v[102:103], v[242:243]
	v_pk_add_f32 v[104:105], v[104:105], v[244:245]
	v_pk_add_f32 v[98:99], v[98:99], v[246:247]
	v_pk_add_f32 v[100:101], v[100:101], v[248:249]
	v_fmac_f32_e32 v130, v102, v102
	v_fmac_f32_e32 v131, v103, v103
	v_fmac_f32_e32 v130, v104, v104
	v_fmac_f32_e32 v131, v105, v105
	v_fmac_f32_e32 v130, v98, v98
	v_fmac_f32_e32 v131, v99, v99
	v_fmac_f32_e32 v130, v100, v100
	v_fmac_f32_e32 v131, v101, v101
	v_cvt_pk_bf16_f32 v102, v102, v103
	v_cvt_pk_bf16_f32 v103, v104, v105
	v_cvt_pk_bf16_f32 v104, v98, v99
	v_cvt_pk_bf16_f32 v105, v100, v101
	global_store_dwordx4 v[132:133], v[102:105], off offset:256
	s_mov_b32 s56, 0x8000
	v_lshl_add_u64 v[132:133], v[132:133], 0, s[56:57]
	v_add_f32_e32 v130, v130, v131
	v_mov_b32_e32 v131, v130
	s_nop 1
	v_permlane16_swap_b32_e32 v130, v131
	s_nop 1
	v_add_f32_e32 v130, v130, v131
	v_mov_b32_e32 v131, v130
	s_nop 1
	v_permlane32_swap_b32_e32 v130, v131
	s_nop 1
	v_add_f32_e32 v130, v130, v131
	s_and_saveexec_b64 s[58:59], s[40:41]
	global_store_dword v[250:251], v130, off
	s_or_b64 exec, exec, s[58:59]
	s_mov_b32 s56, 0x400
	v_lshl_add_u64 v[250:251], v[250:251], 0, s[56:57]
	s_waitcnt vmcnt(17)
	v_lshlrev_b32_e32 v242, 16, v168
	v_and_b32_e32 v243, 0xffff0000, v168
	v_lshlrev_b32_e32 v244, 16, v169
	v_and_b32_e32 v245, 0xffff0000, v169
	v_lshlrev_b32_e32 v246, 16, v170
	v_and_b32_e32 v247, 0xffff0000, v170
	v_lshlrev_b32_e32 v248, 16, v171
	v_and_b32_e32 v249, 0xffff0000, v171
	v_pk_add_f32 v[94:95], v[94:95], v[242:243]
	v_pk_add_f32 v[96:97], v[96:97], v[244:245]
	v_pk_add_f32 v[90:91], v[90:91], v[246:247]
	v_pk_add_f32 v[92:93], v[92:93], v[248:249]
	v_mul_f32_e32 v130, v94, v94
	v_mul_f32_e32 v131, v95, v95
	v_fmac_f32_e32 v130, v96, v96
	v_fmac_f32_e32 v131, v97, v97
	v_fmac_f32_e32 v130, v90, v90
	v_fmac_f32_e32 v131, v91, v91
	v_fmac_f32_e32 v130, v92, v92
	v_fmac_f32_e32 v131, v93, v93
	v_cvt_pk_bf16_f32 v94, v94, v95
	v_cvt_pk_bf16_f32 v95, v96, v97
	v_cvt_pk_bf16_f32 v96, v90, v91
	v_cvt_pk_bf16_f32 v97, v92, v93
	global_store_dwordx4 v[132:133], v[94:97], off
	s_waitcnt vmcnt(17)
	v_lshlrev_b32_e32 v242, 16, v172
	v_and_b32_e32 v243, 0xffff0000, v172
	v_lshlrev_b32_e32 v244, 16, v173
	v_and_b32_e32 v245, 0xffff0000, v173
	v_lshlrev_b32_e32 v246, 16, v174
	v_and_b32_e32 v247, 0xffff0000, v174
	v_lshlrev_b32_e32 v248, 16, v175
	v_and_b32_e32 v249, 0xffff0000, v175
	v_pk_add_f32 v[86:87], v[86:87], v[242:243]
	v_pk_add_f32 v[88:89], v[88:89], v[244:245]
	v_pk_add_f32 v[82:83], v[82:83], v[246:247]
	v_pk_add_f32 v[84:85], v[84:85], v[248:249]
	v_fmac_f32_e32 v130, v86, v86
	v_fmac_f32_e32 v131, v87, v87
	v_fmac_f32_e32 v130, v88, v88
	v_fmac_f32_e32 v131, v89, v89
	v_fmac_f32_e32 v130, v82, v82
	v_fmac_f32_e32 v131, v83, v83
	v_fmac_f32_e32 v130, v84, v84
	v_fmac_f32_e32 v131, v85, v85
	v_cvt_pk_bf16_f32 v86, v86, v87
	v_cvt_pk_bf16_f32 v87, v88, v89
	v_cvt_pk_bf16_f32 v88, v82, v83
	v_cvt_pk_bf16_f32 v89, v84, v85
	global_store_dwordx4 v[132:133], v[86:89], off offset:256
	s_mov_b32 s56, 0x8000
	v_lshl_add_u64 v[132:133], v[132:133], 0, s[56:57]
	v_add_f32_e32 v130, v130, v131
	v_mov_b32_e32 v131, v130
	s_nop 1
	v_permlane16_swap_b32_e32 v130, v131
	s_nop 1
	v_add_f32_e32 v130, v130, v131
	v_mov_b32_e32 v131, v130
	s_nop 1
	v_permlane32_swap_b32_e32 v130, v131
	s_nop 1
	v_add_f32_e32 v130, v130, v131
	s_and_saveexec_b64 s[58:59], s[40:41]
	global_store_dword v[250:251], v130, off
	s_or_b64 exec, exec, s[58:59]
	s_mov_b32 s56, 0x400
	v_lshl_add_u64 v[250:251], v[250:251], 0, s[56:57]
	s_waitcnt vmcnt(18)
	v_lshlrev_b32_e32 v242, 16, v176
	v_and_b32_e32 v243, 0xffff0000, v176
	v_lshlrev_b32_e32 v244, 16, v177
	v_and_b32_e32 v245, 0xffff0000, v177
	v_lshlrev_b32_e32 v246, 16, v178
	v_and_b32_e32 v247, 0xffff0000, v178
	v_lshlrev_b32_e32 v248, 16, v179
	v_and_b32_e32 v249, 0xffff0000, v179
	v_pk_add_f32 v[78:79], v[78:79], v[242:243]
	v_pk_add_f32 v[80:81], v[80:81], v[244:245]
	v_pk_add_f32 v[74:75], v[74:75], v[246:247]
	v_pk_add_f32 v[76:77], v[76:77], v[248:249]
	v_mul_f32_e32 v130, v78, v78
	v_mul_f32_e32 v131, v79, v79
	v_fmac_f32_e32 v130, v80, v80
	v_fmac_f32_e32 v131, v81, v81
	v_fmac_f32_e32 v130, v74, v74
	v_fmac_f32_e32 v131, v75, v75
	v_fmac_f32_e32 v130, v76, v76
	v_fmac_f32_e32 v131, v77, v77
	v_cvt_pk_bf16_f32 v78, v78, v79
	v_cvt_pk_bf16_f32 v79, v80, v81
	v_cvt_pk_bf16_f32 v80, v74, v75
	v_cvt_pk_bf16_f32 v81, v76, v77
	global_store_dwordx4 v[132:133], v[78:81], off
	s_waitcnt vmcnt(18)
	v_lshlrev_b32_e32 v242, 16, v180
	v_and_b32_e32 v243, 0xffff0000, v180
	v_lshlrev_b32_e32 v244, 16, v181
	v_and_b32_e32 v245, 0xffff0000, v181
	v_lshlrev_b32_e32 v246, 16, v182
	v_and_b32_e32 v247, 0xffff0000, v182
	v_lshlrev_b32_e32 v248, 16, v183
	v_and_b32_e32 v249, 0xffff0000, v183
	v_pk_add_f32 v[70:71], v[70:71], v[242:243]
	v_pk_add_f32 v[72:73], v[72:73], v[244:245]
	v_pk_add_f32 v[66:67], v[66:67], v[246:247]
	v_pk_add_f32 v[68:69], v[68:69], v[248:249]
	v_fmac_f32_e32 v130, v70, v70
	v_fmac_f32_e32 v131, v71, v71
	v_fmac_f32_e32 v130, v72, v72
	v_fmac_f32_e32 v131, v73, v73
	v_fmac_f32_e32 v130, v66, v66
	v_fmac_f32_e32 v131, v67, v67
	v_fmac_f32_e32 v130, v68, v68
	v_fmac_f32_e32 v131, v69, v69
	v_cvt_pk_bf16_f32 v70, v70, v71
	v_cvt_pk_bf16_f32 v71, v72, v73
	v_cvt_pk_bf16_f32 v72, v66, v67
	v_cvt_pk_bf16_f32 v73, v68, v69
	global_store_dwordx4 v[132:133], v[70:73], off offset:256
	s_mov_b32 s56, 0x28000
	v_lshl_add_u64 v[132:133], v[132:133], 0, s[56:57]
	v_add_f32_e32 v130, v130, v131
	v_mov_b32_e32 v131, v130
	s_nop 1
	v_permlane16_swap_b32_e32 v130, v131
	s_nop 1
	v_add_f32_e32 v130, v130, v131
	v_mov_b32_e32 v131, v130
	s_nop 1
	v_permlane32_swap_b32_e32 v130, v131
	s_nop 1
	v_add_f32_e32 v130, v130, v131
	s_and_saveexec_b64 s[58:59], s[40:41]
	global_store_dword v[250:251], v130, off
	s_or_b64 exec, exec, s[58:59]
	s_mov_b32 s56, 0x1400
	v_lshl_add_u64 v[250:251], v[250:251], 0, s[56:57]
	s_waitcnt vmcnt(19)
; DI unsigned pk2(float lo, float hi) { f32x2 v = {lo, hi}; bf2_t r = __builtin_convertvector(v, bf2_t); return __builtin_bit_cast(unsigned, r); }
; DI float bflo(unsigned u) { return __uint_as_float(u << 16); }
; DI float bfhi(unsigned u) { return __uint_as_float(u & 0xffff0000u); }
; #define PG8_LAS __attribute__((address_space(3)))
;   DI void operator()(const f32x4 (&acc)[2][2][4][2], const Unit& u, int wr, int wc, int fr, int fq, const PG8_LAS float* sR) const {
;     const int row0 = u.pm * BM + wr * 64 + fr, col0 = u.pn * BM + wc * 32 + 4 * fq;
; #pragma unroll
;     for (int ai = 0; ai < 2; ++ai) {
;       u32x2 sv[4][2][2];
;       if (X0 == nullptr) {
; #pragma unroll
;         for (int m = 0; m < 4; ++m)
; #pragma unroll
;           for (int bj = 0; bj < 2; ++bj)
; #pragma unroll
;             for (int n = 0; n < 2; ++n) sv[m][bj][n] = *(const u32x2*)(S + (size_t)(row0 + ai * HALF + m * 16) * 1024 + col0 + bj * HALF + n * 16);
;       } else {
; #pragma unroll
;         for (int m = 0; m < 4; ++m)
; #pragma unroll
;           for (int bj = 0; bj < 2; ++bj)
; #pragma unroll
;             for (int n = 0; n < 2; ++n) sv[m][bj][n] = (u32x2){0u, 0u};
;       }
; #pragma unroll
;       for (int m = 0; m < 4; ++m) {
;         const int row = row0 + ai * HALF + m * 16;
;         const size_t ro = (size_t)row * 1024 + col0;
;         float ss = 0.f;
; #pragma unroll
;         for (int bj = 0; bj < 2; ++bj)
; #pragma unroll
;           for (int n = 0; n < 2; ++n) {
;             f32x4 v;
;             if (X0 != nullptr) v = *(const f32x4*)(X0 + ro + bj * HALF + n * 16);
;             else { const u32x2 q = sv[m][bj][n]; v[0] = bflo(q[0]); v[1] = bfhi(q[0]); v[2] = bflo(q[1]); v[3] = bfhi(q[1]); }
;             v += acc[ai][bj][m][n];
;             ss += v[0] * v[0] + v[1] * v[1] + v[2] * v[2] + v[3] * v[3];
;             if (!dry) { u32x2 q; q[0] = pk2(v[0], v[1]); q[1] = pk2(v[2], v[3]); *(u32x2*)(S + ro + bj * HALF + n * 16) = q; }
;           }
;         ss += __shfl_xor(ss, 16); ss += __shfl_xor(ss, 32);
;         if (!dry && fq == 0) ssq[(size_t)row * 16 + u.pn * 4 + wc] = ss;
	v_lshlrev_b32_e32 v242, 16, v184
	v_and_b32_e32 v243, 0xffff0000, v184
	v_lshlrev_b32_e32 v244, 16, v185
	v_and_b32_e32 v245, 0xffff0000, v185
	v_lshlrev_b32_e32 v246, 16, v186
	v_and_b32_e32 v247, 0xffff0000, v186
	v_lshlrev_b32_e32 v248, 16, v187
	v_and_b32_e32 v249, 0xffff0000, v187
	v_pk_add_f32 v[62:63], v[62:63], v[242:243]
	v_pk_add_f32 v[64:65], v[64:65], v[244:245]
	v_pk_add_f32 v[58:59], v[58:59], v[246:247]
	v_pk_add_f32 v[60:61], v[60:61], v[248:249]
	v_mul_f32_e32 v130, v62, v62
	v_mul_f32_e32 v131, v63, v63
	v_fmac_f32_e32 v130, v64, v64
	v_fmac_f32_e32 v131, v65, v65
	v_fmac_f32_e32 v130, v58, v58
	v_fmac_f32_e32 v131, v59, v59
	v_fmac_f32_e32 v130, v60, v60
	v_fmac_f32_e32 v131, v61, v61
	v_cvt_pk_bf16_f32 v62, v62, v63
	v_cvt_pk_bf16_f32 v63, v64, v65
	v_cvt_pk_bf16_f32 v64, v58, v59
	v_cvt_pk_bf16_f32 v65, v60, v61
	global_store_dwordx4 v[132:133], v[62:65], off
	s_waitcnt vmcnt(19)
	v_lshlrev_b32_e32 v242, 16, v188
	v_and_b32_e32 v243, 0xffff0000, v188
	v_lshlrev_b32_e32 v244, 16, v189
	v_and_b32_e32 v245, 0xffff0000, v189
	v_lshlrev_b32_e32 v246, 16, v190
	v_and_b32_e32 v247, 0xffff0000, v190
	v_lshlrev_b32_e32 v248, 16, v191
	v_and_b32_e32 v249, 0xffff0000, v191
	v_pk_add_f32 v[54:55], v[54:55], v[242:243]
	v_pk_add_f32 v[56:57], v[56:57], v[244:245]
	v_pk_add_f32 v[50:51], v[50:51], v[246:247]
	v_pk_add_f32 v[52:53], v[52:53], v[248:249]
	v_fmac_f32_e32 v130, v54, v54
	v_fmac_f32_e32 v131, v55, v55
	v_fmac_f32_e32 v130, v56, v56
	v_fmac_f32_e32 v131, v57, v57
	v_fmac_f32_e32 v130, v50, v50
	v_fmac_f32_e32 v131, v51, v51
	v_fmac_f32_e32 v130, v52, v52
	v_fmac_f32_e32 v131, v53, v53
	v_cvt_pk_bf16_f32 v54, v54, v55
	v_cvt_pk_bf16_f32 v55, v56, v57
	v_cvt_pk_bf16_f32 v56, v50, v51
	v_cvt_pk_bf16_f32 v57, v52, v53
	global_store_dwordx4 v[132:133], v[54:57], off offset:256
	s_mov_b32 s56, 0x8000
	v_lshl_add_u64 v[132:133], v[132:133], 0, s[56:57]
	v_add_f32_e32 v130, v130, v131
	v_mov_b32_e32 v131, v130
	s_nop 1
	v_permlane16_swap_b32_e32 v130, v131
	s_nop 1
	v_add_f32_e32 v130, v130, v131
	v_mov_b32_e32 v131, v130
	s_nop 1
	v_permlane32_swap_b32_e32 v130, v131
	s_nop 1
	v_add_f32_e32 v130, v130, v131
	s_and_saveexec_b64 s[58:59], s[40:41]
	global_store_dword v[250:251], v130, off
	s_or_b64 exec, exec, s[58:59]
	s_mov_b32 s56, 0x400
	v_lshl_add_u64 v[250:251], v[250:251], 0, s[56:57]
	s_waitcnt vmcnt(20)
	v_lshlrev_b32_e32 v242, 16, v192
	v_and_b32_e32 v243, 0xffff0000, v192
	v_lshlrev_b32_e32 v244, 16, v193
	v_and_b32_e32 v245, 0xffff0000, v193
	v_lshlrev_b32_e32 v246, 16, v194
	v_and_b32_e32 v247, 0xffff0000, v194
	v_lshlrev_b32_e32 v248, 16, v195
	v_and_b32_e32 v249, 0xffff0000, v195
	v_pk_add_f32 v[46:47], v[46:47], v[242:243]
	v_pk_add_f32 v[48:49], v[48:49], v[244:245]
	v_pk_add_f32 v[42:43], v[42:43], v[246:247]
	v_pk_add_f32 v[44:45], v[44:45], v[248:249]
	v_mul_f32_e32 v130, v46, v46
	v_mul_f32_e32 v131, v47, v47
	v_fmac_f32_e32 v130, v48, v48
	v_fmac_f32_e32 v131, v49, v49
	v_fmac_f32_e32 v130, v42, v42
	v_fmac_f32_e32 v131, v43, v43
	v_fmac_f32_e32 v130, v44, v44
	v_fmac_f32_e32 v131, v45, v45
	v_cvt_pk_bf16_f32 v46, v46, v47
	v_cvt_pk_bf16_f32 v47, v48, v49
	v_cvt_pk_bf16_f32 v48, v42, v43
	v_cvt_pk_bf16_f32 v49, v44, v45
	global_store_dwordx4 v[132:133], v[46:49], off
	s_waitcnt vmcnt(20)
	v_lshlrev_b32_e32 v242, 16, v196
	v_and_b32_e32 v243, 0xffff0000, v196
	v_lshlrev_b32_e32 v244, 16, v197
	v_and_b32_e32 v245, 0xffff0000, v197
	v_lshlrev_b32_e32 v246, 16, v198
	v_and_b32_e32 v247, 0xffff0000, v198
	v_lshlrev_b32_e32 v248, 16, v199
	v_and_b32_e32 v249, 0xffff0000, v199
	v_pk_add_f32 v[38:39], v[38:39], v[242:243]
	v_pk_add_f32 v[40:41], v[40:41], v[244:245]
	v_pk_add_f32 v[34:35], v[34:35], v[246:247]
	v_pk_add_f32 v[36:37], v[36:37], v[248:249]
	v_fmac_f32_e32 v130, v38, v38
	v_fmac_f32_e32 v131, v39, v39
	v_fmac_f32_e32 v130, v40, v40
	v_fmac_f32_e32 v131, v41, v41
	v_fmac_f32_e32 v130, v34, v34
	v_fmac_f32_e32 v131, v35, v35
	v_fmac_f32_e32 v130, v36, v36
	v_fmac_f32_e32 v131, v37, v37
	v_cvt_pk_bf16_f32 v38, v38, v39
	v_cvt_pk_bf16_f32 v39, v40, v41
	v_cvt_pk_bf16_f32 v40, v34, v35
	v_cvt_pk_bf16_f32 v41, v36, v37
	global_store_dwordx4 v[132:133], v[38:41], off offset:256
	s_mov_b32 s56, 0x8000
	v_lshl_add_u64 v[132:133], v[132:133], 0, s[56:57]
	v_add_f32_e32 v130, v130, v131
	v_mov_b32_e32 v131, v130
	s_nop 1
	v_permlane16_swap_b32_e32 v130, v131
	s_nop 1
	v_add_f32_e32 v130, v130, v131
	v_mov_b32_e32 v131, v130
	s_nop 1
	v_permlane32_swap_b32_e32 v130, v131
	s_nop 1
	v_add_f32_e32 v130, v130, v131
	s_and_saveexec_b64 s[58:59], s[40:41]
	global_store_dword v[250:251], v130, off
	s_or_b64 exec, exec, s[58:59]
	s_mov_b32 s56, 0x400
	v_lshl_add_u64 v[250:251], v[250:251], 0, s[56:57]
	s_waitcnt vmcnt(21)
	v_lshlrev_b32_e32 v242, 16, v226
	v_and_b32_e32 v243, 0xffff0000, v226
	v_lshlrev_b32_e32 v244, 16, v227
	v_and_b32_e32 v245, 0xffff0000, v227
	v_lshlrev_b32_e32 v246, 16, v228
	v_and_b32_e32 v247, 0xffff0000, v228
	v_lshlrev_b32_e32 v248, 16, v229
	v_and_b32_e32 v249, 0xffff0000, v229
	v_pk_add_f32 v[30:31], v[30:31], v[242:243]
	v_pk_add_f32 v[32:33], v[32:33], v[244:245]
	v_pk_add_f32 v[26:27], v[26:27], v[246:247]
	v_pk_add_f32 v[28:29], v[28:29], v[248:249]
	v_mul_f32_e32 v130, v30, v30
	v_mul_f32_e32 v131, v31, v31
	v_fmac_f32_e32 v130, v32, v32
	v_fmac_f32_e32 v131, v33, v33
	v_fmac_f32_e32 v130, v26, v26
	v_fmac_f32_e32 v131, v27, v27
	v_fmac_f32_e32 v130, v28, v28
	v_fmac_f32_e32 v131, v29, v29
	v_cvt_pk_bf16_f32 v30, v30, v31
	v_cvt_pk_bf16_f32 v31, v32, v33
	v_cvt_pk_bf16_f32 v32, v26, v27
	v_cvt_pk_bf16_f32 v33, v28, v29
	global_store_dwordx4 v[132:133], v[30:33], off
	s_waitcnt vmcnt(21)
; DI unsigned pk2(float lo, float hi) { f32x2 v = {lo, hi}; bf2_t r = __builtin_convertvector(v, bf2_t); return __builtin_bit_cast(unsigned, r); }
; DI float bflo(unsigned u) { return __uint_as_float(u << 16); }
; DI float bfhi(unsigned u) { return __uint_as_float(u & 0xffff0000u); }
; #define PG8_LAS __attribute__((address_space(3)))
;   DI void operator()(const f32x4 (&acc)[2][2][4][2], const Unit& u, int wr, int wc, int fr, int fq, const PG8_LAS float* sR) const {
;     const int row0 = u.pm * BM + wr * 64 + fr, col0 = u.pn * BM + wc * 32 + 4 * fq;
; #pragma unroll
;     for (int ai = 0; ai < 2; ++ai) {
;       u32x2 sv[4][2][2];
;       if (X0 == nullptr) {
; #pragma unroll
;         for (int m = 0; m < 4; ++m)
; #pragma unroll
;           for (int bj = 0; bj < 2; ++bj)
; #pragma unroll
;             for (int n = 0; n < 2; ++n) sv[m][bj][n] = *(const u32x2*)(S + (size_t)(row0 + ai * HALF + m * 16) * 1024 + col0 + bj * HALF + n * 16);
;       } else {
; #pragma unroll
;         for (int m = 0; m < 4; ++m)
; #pragma unroll
;           for (int bj = 0; bj < 2; ++bj)
; #pragma unroll
;             for (int n = 0; n < 2; ++n) sv[m][bj][n] = (u32x2){0u, 0u};
;       }
; #pragma unroll
;       for (int m = 0; m < 4; ++m) {
;         const int row = row0 + ai * HALF + m * 16;
;         const size_t ro = (size_t)row * 1024 + col0;
;         float ss = 0.f;
; #pragma unroll
;         for (int bj = 0; bj < 2; ++bj)
; #pragma unroll
;           for (int n = 0; n < 2; ++n) {
;             f32x4 v;
;             if (X0 != nullptr) v = *(const f32x4*)(X0 + ro + bj * HALF + n * 16);
;             else { const u32x2 q = sv[m][bj][n]; v[0] = bflo(q[0]); v[1] = bfhi(q[0]); v[2] = bflo(q[1]); v[3] = bfhi(q[1]); }
;             v += acc[ai][bj][m][n];
;             ss += v[0] * v[0] + v[1] * v[1] + v[2] * v[2] + v[3] * v[3];
;             if (!dry) { u32x2 q; q[0] = pk2(v[0], v[1]); q[1] = pk2(v[2], v[3]); *(u32x2*)(S + ro + bj * HALF + n * 16) = q; }
;           }
;         ss += __shfl_xor(ss, 16); ss += __shfl_xor(ss, 32);
;         if (!dry && fq == 0) ssq[(size_t)row * 16 + u.pn * 4 + wc] = ss;
	v_lshlrev_b32_e32 v242, 16, v230
	v_and_b32_e32 v243, 0xffff0000, v230
	v_lshlrev_b32_e32 v244, 16, v231
	v_and_b32_e32 v245, 0xffff0000, v231
	v_lshlrev_b32_e32 v246, 16, v232
	v_and_b32_e32 v247, 0xffff0000, v232
	v_lshlrev_b32_e32 v248, 16, v233
	v_and_b32_e32 v249, 0xffff0000, v233
	v_pk_add_f32 v[22:23], v[22:23], v[242:243]
	v_pk_add_f32 v[24:25], v[24:25], v[244:245]
	v_pk_add_f32 v[18:19], v[18:19], v[246:247]
	v_pk_add_f32 v[20:21], v[20:21], v[248:249]
	v_fmac_f32_e32 v130, v22, v22
	v_fmac_f32_e32 v131, v23, v23
	v_fmac_f32_e32 v130, v24, v24
	v_fmac_f32_e32 v131, v25, v25
	v_fmac_f32_e32 v130, v18, v18
	v_fmac_f32_e32 v131, v19, v19
	v_fmac_f32_e32 v130, v20, v20
	v_fmac_f32_e32 v131, v21, v21
	v_cvt_pk_bf16_f32 v22, v22, v23
	v_cvt_pk_bf16_f32 v23, v24, v25
	v_cvt_pk_bf16_f32 v24, v18, v19
	v_cvt_pk_bf16_f32 v25, v20, v21
	global_store_dwordx4 v[132:133], v[22:25], off offset:256
	s_mov_b32 s56, 0x8000
	v_lshl_add_u64 v[132:133], v[132:133], 0, s[56:57]
	v_add_f32_e32 v130, v130, v131
	v_mov_b32_e32 v131, v130
	s_nop 1
	v_permlane16_swap_b32_e32 v130, v131
	s_nop 1
	v_add_f32_e32 v130, v130, v131
	v_mov_b32_e32 v131, v130
	s_nop 1
	v_permlane32_swap_b32_e32 v130, v131
	s_nop 1
	v_add_f32_e32 v130, v130, v131
	s_and_saveexec_b64 s[58:59], s[40:41]
	global_store_dword v[250:251], v130, off
	s_or_b64 exec, exec, s[58:59]
	s_mov_b32 s56, 0x400
	v_lshl_add_u64 v[250:251], v[250:251], 0, s[56:57]
	s_waitcnt vmcnt(22)
	v_lshlrev_b32_e32 v242, 16, v234
	v_and_b32_e32 v243, 0xffff0000, v234
	v_lshlrev_b32_e32 v244, 16, v235
	v_and_b32_e32 v245, 0xffff0000, v235
	v_lshlrev_b32_e32 v246, 16, v236
	v_and_b32_e32 v247, 0xffff0000, v236
	v_lshlrev_b32_e32 v248, 16, v237
	v_and_b32_e32 v249, 0xffff0000, v237
	v_pk_add_f32 v[14:15], v[14:15], v[242:243]
	v_pk_add_f32 v[16:17], v[16:17], v[244:245]
	v_pk_add_f32 v[10:11], v[10:11], v[246:247]
	v_pk_add_f32 v[12:13], v[12:13], v[248:249]
	v_mul_f32_e32 v130, v14, v14
	v_mul_f32_e32 v131, v15, v15
	v_fmac_f32_e32 v130, v16, v16
	v_fmac_f32_e32 v131, v17, v17
	v_fmac_f32_e32 v130, v10, v10
	v_fmac_f32_e32 v131, v11, v11
	v_fmac_f32_e32 v130, v12, v12
	v_fmac_f32_e32 v131, v13, v13
	v_cvt_pk_bf16_f32 v14, v14, v15
	v_cvt_pk_bf16_f32 v15, v16, v17
	v_cvt_pk_bf16_f32 v16, v10, v11
	v_cvt_pk_bf16_f32 v17, v12, v13
	global_store_dwordx4 v[132:133], v[14:17], off
	s_waitcnt vmcnt(22)
	v_lshlrev_b32_e32 v242, 16, v238
	v_and_b32_e32 v243, 0xffff0000, v238
	v_lshlrev_b32_e32 v244, 16, v239
	v_and_b32_e32 v245, 0xffff0000, v239
	v_lshlrev_b32_e32 v246, 16, v240
	v_and_b32_e32 v247, 0xffff0000, v240
	v_lshlrev_b32_e32 v248, 16, v241
	v_and_b32_e32 v249, 0xffff0000, v241
	v_pk_add_f32 v[6:7], v[6:7], v[242:243]
	v_pk_add_f32 v[8:9], v[8:9], v[244:245]
	v_pk_add_f32 v[2:3], v[2:3], v[246:247]
	v_pk_add_f32 v[4:5], v[4:5], v[248:249]
	v_fmac_f32_e32 v130, v6, v6
	v_fmac_f32_e32 v131, v7, v7
	v_fmac_f32_e32 v130, v8, v8
	v_fmac_f32_e32 v131, v9, v9
	v_fmac_f32_e32 v130, v2, v2
	v_fmac_f32_e32 v131, v3, v3
	v_fmac_f32_e32 v130, v4, v4
	v_fmac_f32_e32 v131, v5, v5
	v_cvt_pk_bf16_f32 v6, v6, v7
	v_cvt_pk_bf16_f32 v7, v8, v9
	v_cvt_pk_bf16_f32 v8, v2, v3
	v_cvt_pk_bf16_f32 v9, v4, v5
	global_store_dwordx4 v[132:133], v[6:9], off offset:256
	v_add_f32_e32 v130, v130, v131
	v_mov_b32_e32 v131, v130
	s_nop 1
	v_permlane16_swap_b32_e32 v130, v131
	s_nop 1
	v_add_f32_e32 v130, v130, v131
	v_mov_b32_e32 v131, v130
	s_nop 1
	v_permlane32_swap_b32_e32 v130, v131
	s_nop 1
	v_add_f32_e32 v130, v130, v131
	s_and_saveexec_b64 s[58:59], s[40:41]
	global_store_dword v[250:251], v130, off
	s_or_b64 exec, exec, s[58:59]
	v_readlane_b32 s4, v253, 56
	v_readlane_b32 s5, v253, 57
	v_readlane_b32 s6, v253, 58
	v_readlane_b32 s7, v253, 59
	v_readlane_b32 s8, v253, 60
	v_readlane_b32 s9, v253, 61
	v_readlane_b32 s10, v253, 62
	v_readlane_b32 s11, v253, 63
	v_readlane_b32 s12, v254, 0
	v_readlane_b32 s13, v254, 1
	v_readlane_b32 s14, v254, 2
	v_readlane_b32 s15, v254, 3
	v_readlane_b32 s16, v254, 4
	v_readlane_b32 s17, v254, 5
	v_readlane_b32 s18, v254, 6
	v_readlane_b32 s19, v254, 7
	s_mov_b64 s[44:45], exec
	s_branch .LBB0_823
.Lres_x0_path:
	v_lshl_add_u32 v152, s78, 8, v222
	v_and_b32_e32 v153, 4, v224
	v_lshl_or_b32 v154, s34, 8, v224
	v_mad_u32_u24 v154, v153, 3, v154
	v_lshlrev_b32_e32 v153, 10, v152
	v_add_u32_e32 v154, v154, v153
	v_mov_b32_e32 v155, 0
	v_lshl_add_u64 v[132:133], v[154:155], 1, s[22:23]
	v_readlane_b32 s4, v253, 56
	v_readlane_b32 s5, v253, 57
	v_lshlrev_b32_e32 v154, 6, v152
	s_lshl_b32 s56, s34, 4
	s_lshl_b32 s57, s70, 2
	s_add_i32 s56, s56, s57
	v_add_u32_e32 v154, s56, v154
	v_lshl_add_u64 v[250:251], v[154:155], 0, s[92:93]
	s_mov_b32 s57, 0
	v_lshl_add_u32 v152, s78, 8, v222
	v_and_b32_e32 v153, 4, v224
	v_lshl_or_b32 v154, s34, 8, v224
	v_mad_u32_u24 v154, v153, 3, v154
	v_lshlrev_b32_e32 v153, 10, v152
	v_add_u32_e32 v154, v154, v153
	v_lshl_add_u64 v[130:131], v[154:155], 2, s[4:5]
	global_load_dwordx4 v[152:155], v[130:131], off
	global_load_dwordx4 v[156:159], v[130:131], off offset:16
	global_load_dwordx4 v[160:163], v[130:131], off offset:512
	global_load_dwordx4 v[164:167], v[130:131], off offset:528
	s_mov_b32 s56, 0x10000
	v_lshl_add_u64 v[130:131], v[130:131], 0, s[56:57]
	global_load_dwordx4 v[168:171], v[130:131], off
	global_load_dwordx4 v[172:175], v[130:131], off offset:16
	global_load_dwordx4 v[176:179], v[130:131], off offset:512
	global_load_dwordx4 v[180:183], v[130:131], off offset:528
	s_mov_b32 s56, 0x10000
	v_lshl_add_u64 v[130:131], v[130:131], 0, s[56:57]
	global_load_dwordx4 v[184:187], v[130:131], off
	global_load_dwordx4 v[188:191], v[130:131], off offset:16
; DI unsigned pk2(float lo, float hi) { f32x2 v = {lo, hi}; bf2_t r = __builtin_convertvector(v, bf2_t); return __builtin_bit_cast(unsigned, r); }
; DI float bflo(unsigned u) { return __uint_as_float(u << 16); }
; DI float bfhi(unsigned u) { return __uint_as_float(u & 0xffff0000u); }
; #define PG8_LAS __attribute__((address_space(3)))
;   DI void operator()(const f32x4 (&acc)[2][2][4][2], const Unit& u, int wr, int wc, int fr, int fq, const PG8_LAS float* sR) const {
;     const int row0 = u.pm * BM + wr * 64 + fr, col0 = u.pn * BM + wc * 32 + 4 * fq;
; #pragma unroll
;     for (int ai = 0; ai < 2; ++ai) {
;       u32x2 sv[4][2][2];
;       if (X0 == nullptr) {
; #pragma unroll
;         for (int m = 0; m < 4; ++m)
; #pragma unroll
;           for (int bj = 0; bj < 2; ++bj)
; #pragma unroll
;             for (int n = 0; n < 2; ++n) sv[m][bj][n] = *(const u32x2*)(S + (size_t)(row0 + ai * HALF + m * 16) * 1024 + col0 + bj * HALF + n * 16);
;       } else {
; #pragma unroll
;         for (int m = 0; m < 4; ++m)
; #pragma unroll
;           for (int bj = 0; bj < 2; ++bj)
; #pragma unroll
;             for (int n = 0; n < 2; ++n) sv[m][bj][n] = (u32x2){0u, 0u};
;       }
; #pragma unroll
;       for (int m = 0; m < 4; ++m) {
;         const int row = row0 + ai * HALF + m * 16;
;         const size_t ro = (size_t)row * 1024 + col0;
;         float ss = 0.f;
; #pragma unroll
;         for (int bj = 0; bj < 2; ++bj)
; #pragma unroll
;           for (int n = 0; n < 2; ++n) {
;             f32x4 v;
;             if (X0 != nullptr) v = *(const f32x4*)(X0 + ro + bj * HALF + n * 16);
;             else { const u32x2 q = sv[m][bj][n]; v[0] = bflo(q[0]); v[1] = bfhi(q[0]); v[2] = bflo(q[1]); v[3] = bfhi(q[1]); }
;             v += acc[ai][bj][m][n];
;             ss += v[0] * v[0] + v[1] * v[1] + v[2] * v[2] + v[3] * v[3];
;             if (!dry) { u32x2 q; q[0] = pk2(v[0], v[1]); q[1] = pk2(v[2], v[3]); *(u32x2*)(S + ro + bj * HALF + n * 16) = q; }
;           }
;         ss += __shfl_xor(ss, 16); ss += __shfl_xor(ss, 32);
;         if (!dry && fq == 0) ssq[(size_t)row * 16 + u.pn * 4 + wc] = ss;
	global_load_dwordx4 v[192:195], v[130:131], off offset:512
	global_load_dwordx4 v[196:199], v[130:131], off offset:528
	s_mov_b32 s56, 0x10000
	v_lshl_add_u64 v[130:131], v[130:131], 0, s[56:57]
	global_load_dwordx4 v[226:229], v[130:131], off
	global_load_dwordx4 v[230:233], v[130:131], off offset:16
	global_load_dwordx4 v[234:237], v[130:131], off offset:512
	global_load_dwordx4 v[238:241], v[130:131], off offset:528
	s_mov_b32 s56, 0x50000
	v_lshl_add_u64 v[130:131], v[130:131], 0, s[56:57]
	v_permlane16_swap_b32_e32 v126, v122
	v_permlane16_swap_b32_e32 v127, v123
	v_permlane16_swap_b32_e32 v128, v124
	v_permlane16_swap_b32_e32 v129, v125
	v_permlane16_swap_b32_e32 v118, v114
	v_permlane16_swap_b32_e32 v119, v115
	v_permlane16_swap_b32_e32 v120, v116
	v_permlane16_swap_b32_e32 v121, v117
	v_permlane16_swap_b32_e32 v110, v106
	v_permlane16_swap_b32_e32 v111, v107
	v_permlane16_swap_b32_e32 v112, v108
	v_permlane16_swap_b32_e32 v113, v109
	v_permlane16_swap_b32_e32 v102, v98
	v_permlane16_swap_b32_e32 v103, v99
	v_permlane16_swap_b32_e32 v104, v100
	v_permlane16_swap_b32_e32 v105, v101
	v_permlane16_swap_b32_e32 v94, v90
	v_permlane16_swap_b32_e32 v95, v91
	v_permlane16_swap_b32_e32 v96, v92
	v_permlane16_swap_b32_e32 v97, v93
	v_permlane16_swap_b32_e32 v86, v82
	v_permlane16_swap_b32_e32 v87, v83
	v_permlane16_swap_b32_e32 v88, v84
	v_permlane16_swap_b32_e32 v89, v85
	v_permlane16_swap_b32_e32 v78, v74
	v_permlane16_swap_b32_e32 v79, v75
	v_permlane16_swap_b32_e32 v80, v76
	v_permlane16_swap_b32_e32 v81, v77
	v_permlane16_swap_b32_e32 v70, v66
	v_permlane16_swap_b32_e32 v71, v67
	v_permlane16_swap_b32_e32 v72, v68
	v_permlane16_swap_b32_e32 v73, v69
	v_permlane16_swap_b32_e32 v62, v58
	v_permlane16_swap_b32_e32 v63, v59
	v_permlane16_swap_b32_e32 v64, v60
	v_permlane16_swap_b32_e32 v65, v61
	v_permlane16_swap_b32_e32 v54, v50
	v_permlane16_swap_b32_e32 v55, v51
	v_permlane16_swap_b32_e32 v56, v52
	v_permlane16_swap_b32_e32 v57, v53
	v_permlane16_swap_b32_e32 v46, v42
	v_permlane16_swap_b32_e32 v47, v43
	v_permlane16_swap_b32_e32 v48, v44
	v_permlane16_swap_b32_e32 v49, v45
	v_permlane16_swap_b32_e32 v38, v34
	v_permlane16_swap_b32_e32 v39, v35
	v_permlane16_swap_b32_e32 v40, v36
	v_permlane16_swap_b32_e32 v41, v37
	v_permlane16_swap_b32_e32 v30, v26
	v_permlane16_swap_b32_e32 v31, v27
	v_permlane16_swap_b32_e32 v32, v28
	v_permlane16_swap_b32_e32 v33, v29
	v_permlane16_swap_b32_e32 v22, v18
	v_permlane16_swap_b32_e32 v23, v19
	v_permlane16_swap_b32_e32 v24, v20
	v_permlane16_swap_b32_e32 v25, v21
	v_permlane16_swap_b32_e32 v14, v10
	v_permlane16_swap_b32_e32 v15, v11
	v_permlane16_swap_b32_e32 v16, v12
	v_permlane16_swap_b32_e32 v17, v13
	v_permlane16_swap_b32_e32 v6, v2
	v_permlane16_swap_b32_e32 v7, v3
	v_permlane16_swap_b32_e32 v8, v4
	v_permlane16_swap_b32_e32 v9, v5
	s_waitcnt vmcnt(14)
	v_pk_add_f32 v[126:127], v[126:127], v[152:153]
	v_pk_add_f32 v[128:129], v[128:129], v[154:155]
	v_pk_add_f32 v[122:123], v[122:123], v[156:157]
	v_pk_add_f32 v[124:125], v[124:125], v[158:159]
	global_load_dwordx4 v[152:155], v[130:131], off
	global_load_dwordx4 v[156:159], v[130:131], off offset:16
	v_mul_f32_e32 v242, v126, v126
	v_mul_f32_e32 v243, v127, v127
	v_fmac_f32_e32 v242, v128, v128
	v_fmac_f32_e32 v243, v129, v129
	v_fmac_f32_e32 v242, v122, v122
	v_fmac_f32_e32 v243, v123, v123
	v_fmac_f32_e32 v242, v124, v124
	v_fmac_f32_e32 v243, v125, v125
	v_cvt_pk_bf16_f32 v126, v126, v127
	v_cvt_pk_bf16_f32 v127, v128, v129
	v_cvt_pk_bf16_f32 v128, v122, v123
	v_cvt_pk_bf16_f32 v129, v124, v125
	global_store_dwordx4 v[132:133], v[126:129], off
	s_waitcnt vmcnt(15)
	v_pk_add_f32 v[118:119], v[118:119], v[160:161]
	v_pk_add_f32 v[120:121], v[120:121], v[162:163]
	v_pk_add_f32 v[114:115], v[114:115], v[164:165]
	v_pk_add_f32 v[116:117], v[116:117], v[166:167]
	global_load_dwordx4 v[160:163], v[130:131], off offset:512
	global_load_dwordx4 v[164:167], v[130:131], off offset:528
	s_mov_b32 s56, 0x10000
	v_lshl_add_u64 v[130:131], v[130:131], 0, s[56:57]
	v_fmac_f32_e32 v242, v118, v118
	v_fmac_f32_e32 v243, v119, v119
	v_fmac_f32_e32 v242, v120, v120
	v_fmac_f32_e32 v243, v121, v121
	v_fmac_f32_e32 v242, v114, v114
	v_fmac_f32_e32 v243, v115, v115
	v_fmac_f32_e32 v242, v116, v116
	v_fmac_f32_e32 v243, v117, v117
	v_cvt_pk_bf16_f32 v118, v118, v119
	v_cvt_pk_bf16_f32 v119, v120, v121
	v_cvt_pk_bf16_f32 v120, v114, v115
	v_cvt_pk_bf16_f32 v121, v116, v117
	global_store_dwordx4 v[132:133], v[118:121], off offset:256
	s_mov_b32 s56, 0x8000
	v_lshl_add_u64 v[132:133], v[132:133], 0, s[56:57]
	v_add_f32_e32 v242, v242, v243
	v_mov_b32_e32 v243, v242
	s_nop 1
	v_permlane16_swap_b32_e32 v242, v243
	s_nop 1
	v_add_f32_e32 v242, v242, v243
	v_mov_b32_e32 v243, v242
	s_nop 1
	v_permlane32_swap_b32_e32 v242, v243
	s_nop 1
	v_add_f32_e32 v242, v242, v243
	s_and_saveexec_b64 s[58:59], s[40:41]
	global_store_dword v[250:251], v242, off
	s_or_b64 exec, exec, s[58:59]
	s_mov_b32 s56, 0x400
	v_lshl_add_u64 v[250:251], v[250:251], 0, s[56:57]
	s_waitcnt vmcnt(17)
	v_pk_add_f32 v[110:111], v[110:111], v[168:169]
	v_pk_add_f32 v[112:113], v[112:113], v[170:171]
	v_pk_add_f32 v[106:107], v[106:107], v[172:173]
	v_pk_add_f32 v[108:109], v[108:109], v[174:175]
	global_load_dwordx4 v[168:171], v[130:131], off
	global_load_dwordx4 v[172:175], v[130:131], off offset:16
	v_mul_f32_e32 v242, v110, v110
	v_mul_f32_e32 v243, v111, v111
	v_fmac_f32_e32 v242, v112, v112
	v_fmac_f32_e32 v243, v113, v113
	v_fmac_f32_e32 v242, v106, v106
	v_fmac_f32_e32 v243, v107, v107
	v_fmac_f32_e32 v242, v108, v108
	v_fmac_f32_e32 v243, v109, v109
	v_cvt_pk_bf16_f32 v110, v110, v111
	v_cvt_pk_bf16_f32 v111, v112, v113
	v_cvt_pk_bf16_f32 v112, v106, v107
	v_cvt_pk_bf16_f32 v113, v108, v109
	global_store_dwordx4 v[132:133], v[110:113], off
	s_waitcnt vmcnt(18)
; DI unsigned pk2(float lo, float hi) { f32x2 v = {lo, hi}; bf2_t r = __builtin_convertvector(v, bf2_t); return __builtin_bit_cast(unsigned, r); }
; DI float bflo(unsigned u) { return __uint_as_float(u << 16); }
; DI float bfhi(unsigned u) { return __uint_as_float(u & 0xffff0000u); }
; #define PG8_LAS __attribute__((address_space(3)))
;   DI void operator()(const f32x4 (&acc)[2][2][4][2], const Unit& u, int wr, int wc, int fr, int fq, const PG8_LAS float* sR) const {
;     const int row0 = u.pm * BM + wr * 64 + fr, col0 = u.pn * BM + wc * 32 + 4 * fq;
; #pragma unroll
;     for (int ai = 0; ai < 2; ++ai) {
;       u32x2 sv[4][2][2];
;       if (X0 == nullptr) {
; #pragma unroll
;         for (int m = 0; m < 4; ++m)
; #pragma unroll
;           for (int bj = 0; bj < 2; ++bj)
; #pragma unroll
;             for (int n = 0; n < 2; ++n) sv[m][bj][n] = *(const u32x2*)(S + (size_t)(row0 + ai * HALF + m * 16) * 1024 + col0 + bj * HALF + n * 16);
;       } else {
; #pragma unroll
;         for (int m = 0; m < 4; ++m)
; #pragma unroll
;           for (int bj = 0; bj < 2; ++bj)
; #pragma unroll
;             for (int n = 0; n < 2; ++n) sv[m][bj][n] = (u32x2){0u, 0u};
;       }
; #pragma unroll
;       for (int m = 0; m < 4; ++m) {
;         const int row = row0 + ai * HALF + m * 16;
;         const size_t ro = (size_t)row * 1024 + col0;
;         float ss = 0.f;
; #pragma unroll
;         for (int bj = 0; bj < 2; ++bj)
; #pragma unroll
;           for (int n = 0; n < 2; ++n) {
;             f32x4 v;
;             if (X0 != nullptr) v = *(const f32x4*)(X0 + ro + bj * HALF + n * 16);
;             else { const u32x2 q = sv[m][bj][n]; v[0] = bflo(q[0]); v[1] = bfhi(q[0]); v[2] = bflo(q[1]); v[3] = bfhi(q[1]); }
;             v += acc[ai][bj][m][n];
;             ss += v[0] * v[0] + v[1] * v[1] + v[2] * v[2] + v[3] * v[3];
;             if (!dry) { u32x2 q; q[0] = pk2(v[0], v[1]); q[1] = pk2(v[2], v[3]); *(u32x2*)(S + ro + bj * HALF + n * 16) = q; }
;           }
;         ss += __shfl_xor(ss, 16); ss += __shfl_xor(ss, 32);
;         if (!dry && fq == 0) ssq[(size_t)row * 16 + u.pn * 4 + wc] = ss;
	v_pk_add_f32 v[102:103], v[102:103], v[176:177]
	v_pk_add_f32 v[104:105], v[104:105], v[178:179]
	v_pk_add_f32 v[98:99], v[98:99], v[180:181]
	v_pk_add_f32 v[100:101], v[100:101], v[182:183]
	global_load_dwordx4 v[176:179], v[130:131], off offset:512
	global_load_dwordx4 v[180:183], v[130:131], off offset:528
	s_mov_b32 s56, 0x10000
	v_lshl_add_u64 v[130:131], v[130:131], 0, s[56:57]
	v_fmac_f32_e32 v242, v102, v102
	v_fmac_f32_e32 v243, v103, v103
	v_fmac_f32_e32 v242, v104, v104
	v_fmac_f32_e32 v243, v105, v105
	v_fmac_f32_e32 v242, v98, v98
	v_fmac_f32_e32 v243, v99, v99
	v_fmac_f32_e32 v242, v100, v100
	v_fmac_f32_e32 v243, v101, v101
	v_cvt_pk_bf16_f32 v102, v102, v103
	v_cvt_pk_bf16_f32 v103, v104, v105
	v_cvt_pk_bf16_f32 v104, v98, v99
	v_cvt_pk_bf16_f32 v105, v100, v101
	global_store_dwordx4 v[132:133], v[102:105], off offset:256
	s_mov_b32 s56, 0x8000
	v_lshl_add_u64 v[132:133], v[132:133], 0, s[56:57]
	v_add_f32_e32 v242, v242, v243
	v_mov_b32_e32 v243, v242
	s_nop 1
	v_permlane16_swap_b32_e32 v242, v243
	s_nop 1
	v_add_f32_e32 v242, v242, v243
	v_mov_b32_e32 v243, v242
	s_nop 1
	v_permlane32_swap_b32_e32 v242, v243
	s_nop 1
	v_add_f32_e32 v242, v242, v243
	s_and_saveexec_b64 s[58:59], s[40:41]
	global_store_dword v[250:251], v242, off
	s_or_b64 exec, exec, s[58:59]
	s_mov_b32 s56, 0x400
	v_lshl_add_u64 v[250:251], v[250:251], 0, s[56:57]
	s_waitcnt vmcnt(20)
	v_pk_add_f32 v[94:95], v[94:95], v[184:185]
	v_pk_add_f32 v[96:97], v[96:97], v[186:187]
	v_pk_add_f32 v[90:91], v[90:91], v[188:189]
	v_pk_add_f32 v[92:93], v[92:93], v[190:191]
	global_load_dwordx4 v[184:187], v[130:131], off
	global_load_dwordx4 v[188:191], v[130:131], off offset:16
	v_mul_f32_e32 v242, v94, v94
	v_mul_f32_e32 v243, v95, v95
	v_fmac_f32_e32 v242, v96, v96
	v_fmac_f32_e32 v243, v97, v97
	v_fmac_f32_e32 v242, v90, v90
	v_fmac_f32_e32 v243, v91, v91
	v_fmac_f32_e32 v242, v92, v92
	v_fmac_f32_e32 v243, v93, v93
	v_cvt_pk_bf16_f32 v94, v94, v95
	v_cvt_pk_bf16_f32 v95, v96, v97
	v_cvt_pk_bf16_f32 v96, v90, v91
	v_cvt_pk_bf16_f32 v97, v92, v93
	global_store_dwordx4 v[132:133], v[94:97], off
	s_waitcnt vmcnt(21)
	v_pk_add_f32 v[86:87], v[86:87], v[192:193]
	v_pk_add_f32 v[88:89], v[88:89], v[194:195]
	v_pk_add_f32 v[82:83], v[82:83], v[196:197]
	v_pk_add_f32 v[84:85], v[84:85], v[198:199]
	global_load_dwordx4 v[192:195], v[130:131], off offset:512
	global_load_dwordx4 v[196:199], v[130:131], off offset:528
	s_mov_b32 s56, 0x10000
	v_lshl_add_u64 v[130:131], v[130:131], 0, s[56:57]
	v_fmac_f32_e32 v242, v86, v86
	v_fmac_f32_e32 v243, v87, v87
	v_fmac_f32_e32 v242, v88, v88
	v_fmac_f32_e32 v243, v89, v89
	v_fmac_f32_e32 v242, v82, v82
	v_fmac_f32_e32 v243, v83, v83
	v_fmac_f32_e32 v242, v84, v84
	v_fmac_f32_e32 v243, v85, v85
	v_cvt_pk_bf16_f32 v86, v86, v87
	v_cvt_pk_bf16_f32 v87, v88, v89
	v_cvt_pk_bf16_f32 v88, v82, v83
	v_cvt_pk_bf16_f32 v89, v84, v85
	global_store_dwordx4 v[132:133], v[86:89], off offset:256
	s_mov_b32 s56, 0x8000
	v_lshl_add_u64 v[132:133], v[132:133], 0, s[56:57]
	v_add_f32_e32 v242, v242, v243
	v_mov_b32_e32 v243, v242
	s_nop 1
	v_permlane16_swap_b32_e32 v242, v243
	s_nop 1
	v_add_f32_e32 v242, v242, v243
	v_mov_b32_e32 v243, v242
	s_nop 1
	v_permlane32_swap_b32_e32 v242, v243
	s_nop 1
	v_add_f32_e32 v242, v242, v243
	s_and_saveexec_b64 s[58:59], s[40:41]
	global_store_dword v[250:251], v242, off
	s_or_b64 exec, exec, s[58:59]
	s_mov_b32 s56, 0x400
	v_lshl_add_u64 v[250:251], v[250:251], 0, s[56:57]
	s_waitcnt vmcnt(23)
	v_pk_add_f32 v[78:79], v[78:79], v[226:227]
	v_pk_add_f32 v[80:81], v[80:81], v[228:229]
	v_pk_add_f32 v[74:75], v[74:75], v[230:231]
	v_pk_add_f32 v[76:77], v[76:77], v[232:233]
	global_load_dwordx4 v[226:229], v[130:131], off
	global_load_dwordx4 v[230:233], v[130:131], off offset:16
	v_mul_f32_e32 v242, v78, v78
	v_mul_f32_e32 v243, v79, v79
	v_fmac_f32_e32 v242, v80, v80
	v_fmac_f32_e32 v243, v81, v81
	v_fmac_f32_e32 v242, v74, v74
	v_fmac_f32_e32 v243, v75, v75
	v_fmac_f32_e32 v242, v76, v76
	v_fmac_f32_e32 v243, v77, v77
	v_cvt_pk_bf16_f32 v78, v78, v79
	v_cvt_pk_bf16_f32 v79, v80, v81
	v_cvt_pk_bf16_f32 v80, v74, v75
	v_cvt_pk_bf16_f32 v81, v76, v77
	global_store_dwordx4 v[132:133], v[78:81], off
	s_waitcnt vmcnt(24)
	v_pk_add_f32 v[70:71], v[70:71], v[234:235]
	v_pk_add_f32 v[72:73], v[72:73], v[236:237]
	v_pk_add_f32 v[66:67], v[66:67], v[238:239]
	v_pk_add_f32 v[68:69], v[68:69], v[240:241]
	global_load_dwordx4 v[234:237], v[130:131], off offset:512
	global_load_dwordx4 v[238:241], v[130:131], off offset:528
	v_fmac_f32_e32 v242, v70, v70
	v_fmac_f32_e32 v243, v71, v71
	v_fmac_f32_e32 v242, v72, v72
	v_fmac_f32_e32 v243, v73, v73
	v_fmac_f32_e32 v242, v66, v66
	v_fmac_f32_e32 v243, v67, v67
	v_fmac_f32_e32 v242, v68, v68
	v_fmac_f32_e32 v243, v69, v69
	v_cvt_pk_bf16_f32 v70, v70, v71
	v_cvt_pk_bf16_f32 v71, v72, v73
	v_cvt_pk_bf16_f32 v72, v66, v67
	v_cvt_pk_bf16_f32 v73, v68, v69
	global_store_dwordx4 v[132:133], v[70:73], off offset:256
	s_mov_b32 s56, 0x28000
	v_lshl_add_u64 v[132:133], v[132:133], 0, s[56:57]
	v_add_f32_e32 v242, v242, v243
	v_mov_b32_e32 v243, v242
	s_nop 1
	v_permlane16_swap_b32_e32 v242, v243
	s_nop 1
	v_add_f32_e32 v242, v242, v243
	v_mov_b32_e32 v243, v242
	s_nop 1
	v_permlane32_swap_b32_e32 v242, v243
	s_nop 1
	v_add_f32_e32 v242, v242, v243
	s_and_saveexec_b64 s[58:59], s[40:41]
	global_store_dword v[250:251], v242, off
	s_or_b64 exec, exec, s[58:59]
	s_mov_b32 s56, 0x1400
	v_lshl_add_u64 v[250:251], v[250:251], 0, s[56:57]
	s_waitcnt vmcnt(26)
; DI unsigned pk2(float lo, float hi) { f32x2 v = {lo, hi}; bf2_t r = __builtin_convertvector(v, bf2_t); return __builtin_bit_cast(unsigned, r); }
; DI float bflo(unsigned u) { return __uint_as_float(u << 16); }
; DI float bfhi(unsigned u) { return __uint_as_float(u & 0xffff0000u); }
; #define PG8_LAS __attribute__((address_space(3)))
;   DI void operator()(const f32x4 (&acc)[2][2][4][2], const Unit& u, int wr, int wc, int fr, int fq, const PG8_LAS float* sR) const {
;     const int row0 = u.pm * BM + wr * 64 + fr, col0 = u.pn * BM + wc * 32 + 4 * fq;
; #pragma unroll
;     for (int ai = 0; ai < 2; ++ai) {
;       u32x2 sv[4][2][2];
;       if (X0 == nullptr) {
; #pragma unroll
;         for (int m = 0; m < 4; ++m)
; #pragma unroll
;           for (int bj = 0; bj < 2; ++bj)
; #pragma unroll
;             for (int n = 0; n < 2; ++n) sv[m][bj][n] = *(const u32x2*)(S + (size_t)(row0 + ai * HALF + m * 16) * 1024 + col0 + bj * HALF + n * 16);
;       } else {
; #pragma unroll
;         for (int m = 0; m < 4; ++m)
; #pragma unroll
;           for (int bj = 0; bj < 2; ++bj)
; #pragma unroll
;             for (int n = 0; n < 2; ++n) sv[m][bj][n] = (u32x2){0u, 0u};
;       }
; #pragma unroll
;       for (int m = 0; m < 4; ++m) {
;         const int row = row0 + ai * HALF + m * 16;
;         const size_t ro = (size_t)row * 1024 + col0;
;         float ss = 0.f;
; #pragma unroll
;         for (int bj = 0; bj < 2; ++bj)
; #pragma unroll
;           for (int n = 0; n < 2; ++n) {
;             f32x4 v;
;             if (X0 != nullptr) v = *(const f32x4*)(X0 + ro + bj * HALF + n * 16);
;             else { const u32x2 q = sv[m][bj][n]; v[0] = bflo(q[0]); v[1] = bfhi(q[0]); v[2] = bflo(q[1]); v[3] = bfhi(q[1]); }
;             v += acc[ai][bj][m][n];
;             ss += v[0] * v[0] + v[1] * v[1] + v[2] * v[2] + v[3] * v[3];
;             if (!dry) { u32x2 q; q[0] = pk2(v[0], v[1]); q[1] = pk2(v[2], v[3]); *(u32x2*)(S + ro + bj * HALF + n * 16) = q; }
;           }
;         ss += __shfl_xor(ss, 16); ss += __shfl_xor(ss, 32);
;         if (!dry && fq == 0) ssq[(size_t)row * 16 + u.pn * 4 + wc] = ss;
	v_pk_add_f32 v[62:63], v[62:63], v[152:153]
	v_pk_add_f32 v[64:65], v[64:65], v[154:155]
	v_pk_add_f32 v[58:59], v[58:59], v[156:157]
	v_pk_add_f32 v[60:61], v[60:61], v[158:159]
	v_mul_f32_e32 v242, v62, v62
	v_mul_f32_e32 v243, v63, v63
	v_fmac_f32_e32 v242, v64, v64
	v_fmac_f32_e32 v243, v65, v65
	v_fmac_f32_e32 v242, v58, v58
	v_fmac_f32_e32 v243, v59, v59
	v_fmac_f32_e32 v242, v60, v60
	v_fmac_f32_e32 v243, v61, v61
	v_cvt_pk_bf16_f32 v62, v62, v63
	v_cvt_pk_bf16_f32 v63, v64, v65
	v_cvt_pk_bf16_f32 v64, v58, v59
	v_cvt_pk_bf16_f32 v65, v60, v61
	global_store_dwordx4 v[132:133], v[62:65], off
	s_waitcnt vmcnt(24)
	v_pk_add_f32 v[54:55], v[54:55], v[160:161]
	v_pk_add_f32 v[56:57], v[56:57], v[162:163]
	v_pk_add_f32 v[50:51], v[50:51], v[164:165]
	v_pk_add_f32 v[52:53], v[52:53], v[166:167]
	v_fmac_f32_e32 v242, v54, v54
	v_fmac_f32_e32 v243, v55, v55
	v_fmac_f32_e32 v242, v56, v56
	v_fmac_f32_e32 v243, v57, v57
	v_fmac_f32_e32 v242, v50, v50
	v_fmac_f32_e32 v243, v51, v51
	v_fmac_f32_e32 v242, v52, v52
	v_fmac_f32_e32 v243, v53, v53
	v_cvt_pk_bf16_f32 v54, v54, v55
	v_cvt_pk_bf16_f32 v55, v56, v57
	v_cvt_pk_bf16_f32 v56, v50, v51
	v_cvt_pk_bf16_f32 v57, v52, v53
	global_store_dwordx4 v[132:133], v[54:57], off offset:256
	s_mov_b32 s56, 0x8000
	v_lshl_add_u64 v[132:133], v[132:133], 0, s[56:57]
	v_add_f32_e32 v242, v242, v243
	v_mov_b32_e32 v243, v242
	s_nop 1
	v_permlane16_swap_b32_e32 v242, v243
	s_nop 1
	v_add_f32_e32 v242, v242, v243
	v_mov_b32_e32 v243, v242
	s_nop 1
	v_permlane32_swap_b32_e32 v242, v243
	s_nop 1
	v_add_f32_e32 v242, v242, v243
	s_and_saveexec_b64 s[58:59], s[40:41]
	global_store_dword v[250:251], v242, off
	s_or_b64 exec, exec, s[58:59]
	s_mov_b32 s56, 0x400
	v_lshl_add_u64 v[250:251], v[250:251], 0, s[56:57]
	s_waitcnt vmcnt(22)
	v_pk_add_f32 v[46:47], v[46:47], v[168:169]
	v_pk_add_f32 v[48:49], v[48:49], v[170:171]
	v_pk_add_f32 v[42:43], v[42:43], v[172:173]
	v_pk_add_f32 v[44:45], v[44:45], v[174:175]
	v_mul_f32_e32 v242, v46, v46
	v_mul_f32_e32 v243, v47, v47
	v_fmac_f32_e32 v242, v48, v48
	v_fmac_f32_e32 v243, v49, v49
	v_fmac_f32_e32 v242, v42, v42
	v_fmac_f32_e32 v243, v43, v43
	v_fmac_f32_e32 v242, v44, v44
	v_fmac_f32_e32 v243, v45, v45
	v_cvt_pk_bf16_f32 v46, v46, v47
	v_cvt_pk_bf16_f32 v47, v48, v49
	v_cvt_pk_bf16_f32 v48, v42, v43
	v_cvt_pk_bf16_f32 v49, v44, v45
	global_store_dwordx4 v[132:133], v[46:49], off
	s_waitcnt vmcnt(20)
	v_pk_add_f32 v[38:39], v[38:39], v[176:177]
	v_pk_add_f32 v[40:41], v[40:41], v[178:179]
	v_pk_add_f32 v[34:35], v[34:35], v[180:181]
	v_pk_add_f32 v[36:37], v[36:37], v[182:183]
	v_fmac_f32_e32 v242, v38, v38
	v_fmac_f32_e32 v243, v39, v39
	v_fmac_f32_e32 v242, v40, v40
	v_fmac_f32_e32 v243, v41, v41
	v_fmac_f32_e32 v242, v34, v34
	v_fmac_f32_e32 v243, v35, v35
	v_fmac_f32_e32 v242, v36, v36
	v_fmac_f32_e32 v243, v37, v37
	v_cvt_pk_bf16_f32 v38, v38, v39
	v_cvt_pk_bf16_f32 v39, v40, v41
	v_cvt_pk_bf16_f32 v40, v34, v35
	v_cvt_pk_bf16_f32 v41, v36, v37
	global_store_dwordx4 v[132:133], v[38:41], off offset:256
	s_mov_b32 s56, 0x8000
	v_lshl_add_u64 v[132:133], v[132:133], 0, s[56:57]
	v_add_f32_e32 v242, v242, v243
	v_mov_b32_e32 v243, v242
	s_nop 1
	v_permlane16_swap_b32_e32 v242, v243
	s_nop 1
	v_add_f32_e32 v242, v242, v243
	v_mov_b32_e32 v243, v242
	s_nop 1
	v_permlane32_swap_b32_e32 v242, v243
	s_nop 1
	v_add_f32_e32 v242, v242, v243
	s_and_saveexec_b64 s[58:59], s[40:41]
	global_store_dword v[250:251], v242, off
	s_or_b64 exec, exec, s[58:59]
	s_mov_b32 s56, 0x400
	v_lshl_add_u64 v[250:251], v[250:251], 0, s[56:57]
	s_waitcnt vmcnt(18)
; DI unsigned pk2(float lo, float hi) { f32x2 v = {lo, hi}; bf2_t r = __builtin_convertvector(v, bf2_t); return __builtin_bit_cast(unsigned, r); }
; DI float bflo(unsigned u) { return __uint_as_float(u << 16); }
; DI float bfhi(unsigned u) { return __uint_as_float(u & 0xffff0000u); }
; #define PG8_LAS __attribute__((address_space(3)))
;   DI void operator()(const f32x4 (&acc)[2][2][4][2], const Unit& u, int wr, int wc, int fr, int fq, const PG8_LAS float* sR) const {
;     const int row0 = u.pm * BM + wr * 64 + fr, col0 = u.pn * BM + wc * 32 + 4 * fq;
; #pragma unroll
;     for (int ai = 0; ai < 2; ++ai) {
;       u32x2 sv[4][2][2];
;       if (X0 == nullptr) {
; #pragma unroll
;         for (int m = 0; m < 4; ++m)
; #pragma unroll
;           for (int bj = 0; bj < 2; ++bj)
; #pragma unroll
;             for (int n = 0; n < 2; ++n) sv[m][bj][n] = *(const u32x2*)(S + (size_t)(row0 + ai * HALF + m * 16) * 1024 + col0 + bj * HALF + n * 16);
;       } else {
; #pragma unroll
;         for (int m = 0; m < 4; ++m)
; #pragma unroll
;           for (int bj = 0; bj < 2; ++bj)
; #pragma unroll
;             for (int n = 0; n < 2; ++n) sv[m][bj][n] = (u32x2){0u, 0u};
;       }
; #pragma unroll
;       for (int m = 0; m < 4; ++m) {
;         const int row = row0 + ai * HALF + m * 16;
;         const size_t ro = (size_t)row * 1024 + col0;
;         float ss = 0.f;
; #pragma unroll
;         for (int bj = 0; bj < 2; ++bj)
; #pragma unroll
;           for (int n = 0; n < 2; ++n) {
;             f32x4 v;
;             if (X0 != nullptr) v = *(const f32x4*)(X0 + ro + bj * HALF + n * 16);
;             else { const u32x2 q = sv[m][bj][n]; v[0] = bflo(q[0]); v[1] = bfhi(q[0]); v[2] = bflo(q[1]); v[3] = bfhi(q[1]); }
;             v += acc[ai][bj][m][n];
;             ss += v[0] * v[0] + v[1] * v[1] + v[2] * v[2] + v[3] * v[3];
;             if (!dry) { u32x2 q; q[0] = pk2(v[0], v[1]); q[1] = pk2(v[2], v[3]); *(u32x2*)(S + ro + bj * HALF + n * 16) = q; }
;           }
;         ss += __shfl_xor(ss, 16); ss += __shfl_xor(ss, 32);
;         if (!dry && fq == 0) ssq[(size_t)row * 16 + u.pn * 4 + wc] = ss;
	v_pk_add_f32 v[30:31], v[30:31], v[184:185]
	v_pk_add_f32 v[32:33], v[32:33], v[186:187]
	v_pk_add_f32 v[26:27], v[26:27], v[188:189]
	v_pk_add_f32 v[28:29], v[28:29], v[190:191]
	v_mul_f32_e32 v242, v30, v30
	v_mul_f32_e32 v243, v31, v31
	v_fmac_f32_e32 v242, v32, v32
	v_fmac_f32_e32 v243, v33, v33
	v_fmac_f32_e32 v242, v26, v26
	v_fmac_f32_e32 v243, v27, v27
	v_fmac_f32_e32 v242, v28, v28
	v_fmac_f32_e32 v243, v29, v29
	v_cvt_pk_bf16_f32 v30, v30, v31
	v_cvt_pk_bf16_f32 v31, v32, v33
	v_cvt_pk_bf16_f32 v32, v26, v27
	v_cvt_pk_bf16_f32 v33, v28, v29
	global_store_dwordx4 v[132:133], v[30:33], off
	s_waitcnt vmcnt(16)
	v_pk_add_f32 v[22:23], v[22:23], v[192:193]
	v_pk_add_f32 v[24:25], v[24:25], v[194:195]
	v_pk_add_f32 v[18:19], v[18:19], v[196:197]
	v_pk_add_f32 v[20:21], v[20:21], v[198:199]
	v_fmac_f32_e32 v242, v22, v22
	v_fmac_f32_e32 v243, v23, v23
	v_fmac_f32_e32 v242, v24, v24
	v_fmac_f32_e32 v243, v25, v25
	v_fmac_f32_e32 v242, v18, v18
	v_fmac_f32_e32 v243, v19, v19
	v_fmac_f32_e32 v242, v20, v20
	v_fmac_f32_e32 v243, v21, v21
	v_cvt_pk_bf16_f32 v22, v22, v23
	v_cvt_pk_bf16_f32 v23, v24, v25
	v_cvt_pk_bf16_f32 v24, v18, v19
	v_cvt_pk_bf16_f32 v25, v20, v21
	global_store_dwordx4 v[132:133], v[22:25], off offset:256
	s_mov_b32 s56, 0x8000
	v_lshl_add_u64 v[132:133], v[132:133], 0, s[56:57]
	v_add_f32_e32 v242, v242, v243
	v_mov_b32_e32 v243, v242
	s_nop 1
	v_permlane16_swap_b32_e32 v242, v243
	s_nop 1
	v_add_f32_e32 v242, v242, v243
	v_mov_b32_e32 v243, v242
	s_nop 1
	v_permlane32_swap_b32_e32 v242, v243
	s_nop 1
	v_add_f32_e32 v242, v242, v243
	s_and_saveexec_b64 s[58:59], s[40:41]
	global_store_dword v[250:251], v242, off
	s_or_b64 exec, exec, s[58:59]
	s_mov_b32 s56, 0x400
	v_lshl_add_u64 v[250:251], v[250:251], 0, s[56:57]
	s_waitcnt vmcnt(14)
	v_pk_add_f32 v[14:15], v[14:15], v[226:227]
	v_pk_add_f32 v[16:17], v[16:17], v[228:229]
	v_pk_add_f32 v[10:11], v[10:11], v[230:231]
	v_pk_add_f32 v[12:13], v[12:13], v[232:233]
	v_mul_f32_e32 v242, v14, v14
	v_mul_f32_e32 v243, v15, v15
	v_fmac_f32_e32 v242, v16, v16
	v_fmac_f32_e32 v243, v17, v17
	v_fmac_f32_e32 v242, v10, v10
	v_fmac_f32_e32 v243, v11, v11
	v_fmac_f32_e32 v242, v12, v12
	v_fmac_f32_e32 v243, v13, v13
	v_cvt_pk_bf16_f32 v14, v14, v15
	v_cvt_pk_bf16_f32 v15, v16, v17
	v_cvt_pk_bf16_f32 v16, v10, v11
	v_cvt_pk_bf16_f32 v17, v12, v13
	global_store_dwordx4 v[132:133], v[14:17], off
	s_waitcnt vmcnt(12)
	v_pk_add_f32 v[6:7], v[6:7], v[234:235]
	v_pk_add_f32 v[8:9], v[8:9], v[236:237]
	v_pk_add_f32 v[2:3], v[2:3], v[238:239]
	v_pk_add_f32 v[4:5], v[4:5], v[240:241]
	v_fmac_f32_e32 v242, v6, v6
	v_fmac_f32_e32 v243, v7, v7
	v_fmac_f32_e32 v242, v8, v8
	v_fmac_f32_e32 v243, v9, v9
	v_fmac_f32_e32 v242, v2, v2
	v_fmac_f32_e32 v243, v3, v3
	v_fmac_f32_e32 v242, v4, v4
	v_fmac_f32_e32 v243, v5, v5
	v_cvt_pk_bf16_f32 v6, v6, v7
	v_cvt_pk_bf16_f32 v7, v8, v9
	v_cvt_pk_bf16_f32 v8, v2, v3
	v_cvt_pk_bf16_f32 v9, v4, v5
	global_store_dwordx4 v[132:133], v[6:9], off offset:256
	v_add_f32_e32 v242, v242, v243
	v_mov_b32_e32 v243, v242
	s_nop 1
	v_permlane16_swap_b32_e32 v242, v243
	s_nop 1
	v_add_f32_e32 v242, v242, v243
	v_mov_b32_e32 v243, v242
	s_nop 1
	v_permlane32_swap_b32_e32 v242, v243
	s_nop 1
	v_add_f32_e32 v242, v242, v243
	s_and_saveexec_b64 s[58:59], s[40:41]
	global_store_dword v[250:251], v242, off
	s_or_b64 exec, exec, s[58:59]
	v_readlane_b32 s4, v253, 56
	v_readlane_b32 s5, v253, 57
	v_readlane_b32 s6, v253, 58
	v_readlane_b32 s7, v253, 59
	v_readlane_b32 s8, v253, 60
	v_readlane_b32 s9, v253, 61
	v_readlane_b32 s10, v253, 62
	v_readlane_b32 s11, v253, 63
	v_readlane_b32 s12, v254, 0
	v_readlane_b32 s13, v254, 1
	v_readlane_b32 s14, v254, 2
	v_readlane_b32 s15, v254, 3
	v_readlane_b32 s16, v254, 4
	v_readlane_b32 s17, v254, 5
	v_readlane_b32 s18, v254, 6
	v_readlane_b32 s19, v254, 7
	s_mov_b64 s[44:45], exec
	s_branch .LBB0_823

; DI int otid() { int t = threadIdx.x; asm volatile("" : "+v"(t)); return t; }
; DI void ssd_scan_phase(bf16_t* P, const bf16_t* BT, const bf16_t* Cc, const bf16_t* CB, const float* dt, const float* acs,
;                        const float* cw, const float* cb, const float* Dp, char* lds, bool dry, int mode, float* Sbuf) {
;     ...
;   const int tid = otid(), lane = tid & 63, wave = tid >> 6, h = lane >> 5, l31 = lane & 31;
;   const int r0_ = tid >> 4, cch_ = tid & 15, r0 = r0_, cch = cch_;
;   const int xl_ = 2 * ((tid - 256) & 63), xc_ = (tid - 256) >> 6, xl = xl_, xc = xc_;
;   for (int item0 = blockIdx.x; item0 < 256; item0 += gridDim.x) {
;     const int item = item0 & 127, seg = item0 >> 7, c0 = mode ? seg * 16 : seg * 32, c1 = c0 + (mode ? 16 : 32);
;     const bool zero_init = (mode == 1) || (seg == 0);
;     const int grp = item & 7, mem = (item >> 3) & 15, b = grp >> 2, g = grp & 3, hh = 8 * g + (mem >> 1), ph = mem & 1;
;     const int pcol = hh * 64 + ph * 32;
;     const float Dh = Dp[hh];
;     f32x16 st;
; #pragma unroll
;     for (int i = 0; i < 16; ++i) st[i] = 0.f;
;     if (zero_init) { for (int q = tid; q < 2048; q += 512) ((unsigned*)sSt)[q] = 0u; }
;     else if (wave >= 4) {
;       float dsum = 0.f;
;       for (int cc = 16; cc < 32; ++cc) dsum += acs[((size_t)b * SEQ + cc * 128 + 127) * 32 + hh];
;       const float Db = __expf(dsum);
;       const float* spa = Sbuf + ((size_t)item * 4 + (wave - 4)) * 1024 + lane * 16;
;       const float* spb = spa + (size_t)128 * 4 * 1024;
; #pragma unroll
;       for (int gi = 0; gi < 4; ++gi) { const f32x4 va = *(const f32x4*)(spa + 4 * gi), vb = *(const f32x4*)(spb + 4 * gi); const f32x4 v = va * Db + vb;
;         st[4 * gi] = v[0]; st[4 * gi + 1] = v[1]; st[4 * gi + 2] = v[2]; st[4 * gi + 3] = v[3];
;         u32x2 ov; ov[0] = pk2(v[0], v[1]); ov[1] = pk2(v[2], v[3]);
;         *(u32x2*)(sSt + l31 * 256 + (((4 * (wave - 4) + gi) ^ (l31 & 15)) << 4) + 8 * h) = ov; }
;     }
;     if (tid < 160) sCw[tid] = (tid < 128) ? cw[(tid >> 5) * 3072 + pcol + (tid & 31)] : cb[pcol + tid - 128];
;     const size_t tb = (size_t)b * SEQ, tbs = tb + (size_t)c0 * 128;
;     const size_t cbi0 = ((size_t)(b * 64) * 4 + g) * 16384;
;     const unsigned toff = r0 * 128 + cch * 8;
;     const unsigned xoff = xl * 5120 + xc * 8;
;     const unsigned zoff = (32 * (wave & 3) + l31) * 5120 + 4 * h;
.LBB0_1009:
	v_readlane_b32 s0, v252, 37
	v_readlane_b32 s1, v252, 38
	s_movk_i32 s48, 0x80
	v_mov_b32_e32 v127, v200
	s_andn2_b64 vcc, exec, s[0:1]
	s_cbranch_vccnz .LBB0_1121
	v_readlane_b32 s2, v255, 18
	s_mul_i32 s0, s2, 0xc000
	v_readlane_b32 s4, v253, 34
	s_mul_hi_u32 s1, s2, 0xc000
	v_readlane_b32 s5, v253, 35
	s_add_u32 s0, s4, s0
	s_mul_i32 s34, s2, 0xc00
	v_readlane_b32 s6, v253, 36
	s_addc_u32 s1, s5, s1
	s_lshl_b64 s[30:31], s[34:35], 2
	v_readlane_b32 s7, v253, 37
	s_add_u32 s30, s6, s30
	s_addc_u32 s31, s7, s31
	s_lshl_b32 s34, s2, 5
	v_readlane_b32 s12, v253, 42
	s_lshl_b64 s[40:41], s[34:35], 2
	v_readlane_b32 s13, v253, 43
	s_add_u32 s58, s12, s40
	s_addc_u32 s59, s13, s41
	v_readlane_b32 s2, v255, 23
	s_cmp_lg_u32 s2, 10
	s_cselect_b64 s[60:61], -1, 0
	s_cmp_eq_u32 s2, 10
	s_cselect_b64 s[62:63], -1, 0
	v_bfe_u32 v133, v127, 5, 1
	v_and_b32_e32 v175, 31, v127
	s_waitcnt vmcnt(0)
	v_add_u32_e32 v2, 0xffffff00, v127
	v_lshlrev_b32_e32 v3, 1, v127
	s_and_b64 s[40:41], s[62:63], exec
	v_lshrrev_b32_e32 v178, 1, v2
	v_and_b32_e32 v178, 0x7e, v178
	v_and_b32_e32 v179, 3, v2
	s_cselect_b32 s28, 16, 32
	s_cselect_b32 s37, 4, 5
	v_lshlrev_b32_e32 v3, 8, v175
	s_add_i32 s34, 0, 0x1c000
	v_lshlrev_b32_e32 v5, 3, v133
	v_lshlrev_b32_e32 v6, 2, v127
	v_readlane_b32 s4, v255, 5
	v_readlane_b32 s8, v253, 38
	v_readlane_b32 s9, v253, 39
	v_readlane_b32 s10, v253, 40
	v_readlane_b32 s11, v253, 41
	v_readlane_b32 s14, v253, 44
	v_readlane_b32 s15, v253, 45
	v_readlane_b32 s16, v253, 46
	v_readlane_b32 s17, v253, 47
	v_readlane_b32 s18, v253, 48
	v_readlane_b32 s19, v253, 49
	v_ashrrev_i32_e32 v2, 6, v127
	v_add3_u32 v180, s34, v3, v5
	v_lshrrev_b32_e32 v3, 5, v127
	v_add_u32_e32 v182, s4, v6
	v_lshlrev_b32_e32 v128, 3, v179
	s_movk_i32 s4, 0x1400
	v_and_b32_e32 v177, 15, v127
	v_mul_lo_u32 v3, v3, s91
	v_mad_u32_u24 v130, v178, s4, v128
	v_lshlrev_b32_e32 v183, 5, v2
	s_movk_i32 s52, 0x60
	v_readlane_b32 s4, v253, 16
	v_ashrrev_i32_e32 v176, 4, v127
	v_cmp_gt_i32_e64 s[40:41], 4, v2
	v_cmp_lt_i32_e64 s[42:43], 3, v2
	v_add_u32_e32 v120, -4, v2
	v_or_b32_e32 v181, v3, v175
	v_lshlrev_b32_e32 v3, 3, v177
	v_and_or_b32 v2, v183, s52, v175
	v_readlane_b32 s5, v253, 17
	v_lshl_or_b32 v124, v176, 7, v3
	v_mul_u32_u24_e32 v2, 0x1400, v2
	v_mov_b32_e32 v125, v1
	v_readlane_b32 s4, v252, 44
	v_lshl_or_b32 v132, v133, 2, v2
	v_lshlrev_b64 v[2:3], 1, v[124:125]
	v_readlane_b32 s5, v252, 45
	v_readlane_b32 s16, v253, 28
	v_readlane_b32 s17, v253, 29
	v_lshl_add_u64 v[146:147], s[4:5], 0, v[2:3]
	v_readlane_b32 s4, v255, 6
	v_lshl_add_u64 v[142:143], s[16:17], 0, v[2:3]
	v_lshl_add_u64 v[144:145], s[20:21], 0, v[2:3]
	v_lshlrev_b32_e32 v2, 5, v127
	v_add_u32_e32 v184, s4, v6
	v_readlane_b32 s4, v255, 7
	v_ashrrev_i32_e32 v3, 31, v2
	v_or_b32_e32 v187, v183, v175
	v_add_u32_e32 v185, s4, v6
	s_movk_i32 s4, 0x50
	v_mov_b32_e32 v121, v1
	v_readlane_b32 s2, v252, 42
	v_lshlrev_b64 v[148:149], 2, v[2:3]
	v_mul_lo_u32 v2, v187, s4
	v_and_b32_e32 v0, 63, v127
	v_readlane_b32 s3, v252, 43
	v_add_u32_e32 v7, s33, v2
	v_lshlrev_b64 v[2:3], 12, v[120:121]
	v_lshlrev_b32_e32 v0, 6, v0
	v_lshlrev_b32_e32 v4, 2, v120
	v_lshl_add_u64 v[2:3], s[2:3], 0, v[2:3]
	v_lshl_add_u64 v[122:123], s[2:3], 0, v[0:1]
	v_lshl_add_u64 v[154:155], v[2:3], 0, v[0:1]
	v_bitop3_b32 v0, v4, v127, 15 bitop3:0x78
	v_lshlrev_b32_e32 v121, 4, v0
	v_bitop3_b32 v0, v4, v177, 1 bitop3:0x36
	v_lshlrev_b32_e32 v188, 4, v0
	v_bitop3_b32 v0, v4, v177, 2 bitop3:0x36
	s_movk_i32 s44, 0x800
	s_movk_i32 s46, 0xa0
	s_add_i32 s84, 0, 0x10000
	v_lshlrev_b32_e32 v189, 4, v0
	v_bitop3_b32 v0, v4, v177, 3 bitop3:0x36
	v_cmp_gt_i32_e64 s[44:45], s44, v127
	v_cmp_gt_i32_e64 s[46:47], s46, v127
	v_cmp_gt_i32_e64 s[48:49], s48, v127
	v_cmp_lt_i32_e64 s[50:51], s85, v127
	v_mul_u32_u24_e32 v126, 0x1400, v178
	v_ashrrev_i32_e32 v129, 31, v128
	s_nor_b64 s[64:65], s[62:63], s[42:43]
	v_lshl_add_u64 v[150:151], s[26:27], 0, v[148:149]
	v_lshl_add_u64 v[152:153], s[24:25], 0, v[148:149]
	v_mov_b32_e32 v131, v1
	v_lshl_add_u32 v186, v120, 13, s84
	s_and_b64 s[66:67], s[62:63], s[42:43]
	v_lshlrev_b32_e32 v190, 4, v0
	v_cmp_lt_u32_e64 s[52:53], 2, v178
	v_add_u32_e32 v191, s34, v6
	v_cmp_ne_u32_e64 s[54:55], 0, v178
	v_add_u32_e32 v192, 0xfffffe00, v127
	v_add_u32_e32 v193, v7, v5
	v_readlane_b32 s68, v255, 15
	v_readlane_b32 s6, v253, 18
	v_readlane_b32 s7, v253, 19
	v_readlane_b32 s8, v253, 20
	v_readlane_b32 s9, v253, 21
	v_readlane_b32 s10, v253, 22
	v_readlane_b32 s11, v253, 23
	v_readlane_b32 s12, v253, 24
	v_readlane_b32 s13, v253, 25
	v_readlane_b32 s14, v253, 26
	v_readlane_b32 s15, v253, 27
	v_readlane_b32 s18, v253, 30
	v_readlane_b32 s19, v253, 31
	v_readlane_b32 s69, v255, 16
	s_branch .LBB0_1012

; #define MFMA(a, b, c) __builtin_amdgcn_mfma_f32_32x32x16_bf16((a), (b), (c), 0, 0, 0)
; DI unsigned pk2(float lo, float hi) { f32x2 v = {lo, hi}; bf2_t r = __builtin_convertvector(v, bf2_t); return __builtin_bit_cast(unsigned, r); }
; DI void ssd_scan_phase(bf16_t* P, const bf16_t* BT, const bf16_t* Cc, const bf16_t* CB, const float* dt, const float* acs,
;                        const float* cw, const float* cb, const float* Dp, char* lds, bool dry, int mode, float* Sbuf) {
;     ...
;         const int nt = wave - 4;
;         const float dec = __expf(cAcs[127]);
; #pragma unroll
;         for (int i = 0; i < 16; ++i) st[i] *= dec;
; #pragma unroll
;         for (int kk = 0; kk < 8; ++kk) {
;           const bf16x8 xf = *(const bf16x8*)(sBT + swz128(32 * nt + lq, 2 * kk + hq));
;           const bf16x8 yf = *(const bf16x8*)(sXds + swz128(lq, 2 * kk + hq));
;           st = MFMA(xf, yf, st);
;         }
;         char* stn = sSt + ((c + 1) & 1) * 8192;
; #pragma unroll
;         for (int gi = 0; gi < 4; ++gi) {
;           u32x2 ov; ov[0] = pk2(st[4 * gi], st[4 * gi + 1]); ov[1] = pk2(st[4 * gi + 2], st[4 * gi + 3]);
;           *(u32x2*)(stn + l31 * 256 + (((4 * nt + gi) ^ (l31 & 15)) << 4) + 8 * h) = ov;
;         }
.LBB0_1106:
.LBB0_1107:
	s_andn2_saveexec_b64 s[80:81], s[80:81]
	s_cbranch_execz .LBB0_1109
	v_mov_b32_e32 v20, s88
	ds_read_b32 v250, v20 offset:508
	s_add_i32 s82, 0, 0x1a000
	v_lshlrev_b32_e32 v20, 8, v174
	v_add_u32_e32 v28, v186, v20
	v_add_u32_e32 v29, s82, v20
	v_bitop3_b32 v20, v174, v197, 15 bitop3:0x6c
	v_lshlrev_b32_e32 v24, 4, v20
	v_add_u32_e32 v251, v28, v24
	v_add_u32_e32 v231, v29, v24
	s_and_b32 s82, s85, 0x2000
	ds_read_b128 v[20:23], v251
	ds_read_b128 v[24:27], v231
	v_xor_b32_e32 v230, 0x20, v251
	ds_read_b128 v[28:31], v230
	v_xor_b32_e32 v230, 0x20, v231
	ds_read_b128 v[32:35], v230
	v_xor_b32_e32 v230, 0x40, v251
	ds_read_b128 v[36:39], v230
	v_xor_b32_e32 v230, 0x40, v231
	ds_read_b128 v[40:43], v230
	v_xor_b32_e32 v230, 0x60, v251
	ds_read_b128 v[44:47], v230
	v_xor_b32_e32 v230, 0x60, v231
	ds_read_b128 v[48:51], v230
	v_xor_b32_e32 v230, 0x80, v251
	ds_read_b128 v[222:225], v230
	v_xor_b32_e32 v230, 0x80, v231
	ds_read_b128 v[226:229], v230
	v_xor_b32_e32 v230, 0xa0, v251
	ds_read_b128 v[234:237], v230
	v_xor_b32_e32 v230, 0xa0, v231
	ds_read_b128 v[238:241], v230
	v_xor_b32_e32 v230, 0xc0, v251
	ds_read_b128 v[242:245], v230
	v_xor_b32_e32 v230, 0xc0, v231
	ds_read_b128 v[246:249], v230
	s_waitcnt lgkmcnt(14)
	v_mul_f32_e32 v250, 0x3fb8aa3b, v250
	v_exp_f32_e32 v250, v250
	s_nop 0
	v_pk_mul_f32 v[18:19], v[18:19], v[250:251] op_sel_hi:[1,0]
	v_pk_mul_f32 v[16:17], v[16:17], v[250:251] op_sel_hi:[1,0]
	v_pk_mul_f32 v[14:15], v[14:15], v[250:251] op_sel_hi:[1,0]
	v_pk_mul_f32 v[12:13], v[12:13], v[250:251] op_sel_hi:[1,0]
	v_pk_mul_f32 v[10:11], v[10:11], v[250:251] op_sel_hi:[1,0]
	v_pk_mul_f32 v[8:9], v[8:9], v[250:251] op_sel_hi:[1,0]
	v_pk_mul_f32 v[6:7], v[6:7], v[250:251] op_sel_hi:[1,0]
	v_pk_mul_f32 v[4:5], v[4:5], v[250:251] op_sel_hi:[1,0]
	s_nop 1
	s_waitcnt lgkmcnt(12)
	v_mfma_f32_32x32x16_bf16 v[4:19], v[20:23], v[24:27], v[4:19]
	v_xor_b32_e32 v230, 0xe0, v251
	ds_read_b128 v[20:23], v230
	v_xor_b32_e32 v230, 0xe0, v231
	ds_read_b128 v[24:27], v230
	s_waitcnt lgkmcnt(12)
	v_mfma_f32_32x32x16_bf16 v[4:19], v[28:31], v[32:35], v[4:19]
	s_waitcnt lgkmcnt(10)
	v_mfma_f32_32x32x16_bf16 v[4:19], v[36:39], v[40:43], v[4:19]
	s_waitcnt lgkmcnt(8)
	v_mfma_f32_32x32x16_bf16 v[4:19], v[44:47], v[48:51], v[4:19]
	s_waitcnt lgkmcnt(6)
	v_mfma_f32_32x32x16_bf16 v[4:19], v[222:225], v[226:229], v[4:19]
	s_waitcnt lgkmcnt(4)
	v_mfma_f32_32x32x16_bf16 v[4:19], v[234:237], v[238:241], v[4:19]
	s_waitcnt lgkmcnt(2)
	v_mfma_f32_32x32x16_bf16 v[4:19], v[242:245], v[246:249], v[4:19]
	s_waitcnt lgkmcnt(0)
	v_mfma_f32_32x32x16_bf16 v[4:19], v[20:23], v[24:27], v[4:19]
	v_add_u32_e32 v22, s82, v180
	v_add_u32_e32 v23, v22, v121
	s_nop 9
	v_cvt_pk_bf16_f32 v20, v4, v5
	v_cvt_pk_bf16_f32 v21, v6, v7
	ds_write_b64 v23, v[20:21]
	v_cvt_pk_bf16_f32 v20, v8, v9
	v_cvt_pk_bf16_f32 v21, v10, v11
	v_add_u32_e32 v23, v22, v188
	ds_write_b64 v23, v[20:21]
	v_cvt_pk_bf16_f32 v20, v12, v13
	v_cvt_pk_bf16_f32 v21, v14, v15
	v_add_u32_e32 v23, v22, v189
	ds_write_b64 v23, v[20:21]
	v_cvt_pk_bf16_f32 v20, v16, v17
	v_cvt_pk_bf16_f32 v21, v18, v19
	v_add_u32_e32 v22, v22, v190
	ds_write_b64 v22, v[20:21]
